# v26 + redundant s_setprio 0/1 pairs between the two 16-MFMA blocks of each GEMM sub-phase removed
# baseline (speedup 1.0000x reference)
; DI const char* a_of(const Gemm& g, const Unit& u) { return (const char*)(g.A + (size_t)u.pz * g.zA + (size_t)u.pm * BM * g.lda); }
; DI const char* b_of(const Gemm& g, const Unit& u) { return (const char*)(g.Bt + (size_t)u.pz * g.zB + (size_t)u.pn * BM * g.ldb); }
; #define PG8_STAGE(bufoff, gbase, voff) do { _Pragma("unroll") for (int _i = 0; _i < 2; ++_i) \
;         __builtin_amdgcn_global_load_lds((const unsigned*)((const char*)(gbase) + (voff)[_i]), (LAS unsigned*)(lds + (bufoff) + ldsw + _i * 8192), 16, 0, 0); } while (0)
; #define PG8_LDA(dst, b, h) do { _Pragma("unroll") for (int m = 0; m < 4; ++m) _Pragma("unroll") for (int k = 0; k < 2; ++k) dst[m][k] = *(const LAS bf16x8*)(lds + PG8_SA(b, h) + aoff + m * 2048 + k * 1024); } while (0)
; #define PG8_LDB(dst, b, h) do { _Pragma("unroll") for (int n = 0; n < 2; ++n) _Pragma("unroll") for (int k = 0; k < 2; ++k) dst[n][k] = *(const LAS bf16x8*)(lds + PG8_SB(b, h) + boff + n * 2048 + k * 1024); } while (0)
; #define PG8_WAIT_V(n) asm volatile("s_waitcnt vmcnt(" #n ")" ::: "memory")
; #define PG8_WAIT_L(n) asm volatile("s_waitcnt lgkmcnt(" #n ")" ::: "memory")
; #define PG8_BAR __builtin_amdgcn_s_barrier()
; template <class Epi>
; DI void gemm_phase(LAS unsigned char* lds, int tid, const Gemm g, const Order& S, const Epi& E) {
;     ...
;         const bool has_next = S.next(ui + 1, nxt);
;         const char* nA = has_next ? a_of(g, nxt) : cA; const char* nB = has_next ? b_of(g, nxt) : cB;
; #pragma unroll 1
;         for (int t = 0; t < nt; t += 2) {
;             const bool last = (t == nt - 2);
;             const char* a1 = cA + (size_t)(t + 1) * kstep;
;             const char* a2 = last ? nA : cA + (size_t)(t + 2) * kstep; const char* b2 = last ? nB : cB + (size_t)(t + 2) * kstep;
;             const char* a3 = a2 + kstep; const char* b3 = b2 + kstep;
;             PG8_LDB(B0, 0, 0); PG8_LDB(B1, 0, 1); PG8_SCHED; PG8_LDA(At, 0, 0); PG8_STAGE(PG8_SA(1, 1), a1 + hstepA, voffA);
;             PG8_WAIT_V(8); PG8_WAIT_L(0); PG8_BAR; PG8_MMA(0, 0, At, B0); PG8_MMA(0, 1, At, B1); PG8_BAR; PG8_SCHED;
;             PG8_LDA(At, 0, 1); PG8_STAGE(PG8_SB(0, 0), b2, voffB); PG8_STAGE(PG8_SB(0, 1), b2 + hstepB, voffB); PG8_STAGE(PG8_SA(0, 0), a2, voffA);
;             PG8_WAIT_V(8); PG8_WAIT_L(0); PG8_BAR; PG8_MMA(1, 0, At, B0); PG8_MMA(1, 1, At, B1); PG8_BAR; PG8_SCHED;
.LBB0_387:
	s_add_u32 s12, s8, 0xfffc0080
	s_addc_u32 s13, s9, -1
	s_add_i32 s29, 0, 0x10000
	s_cmp_eq_u32 s81, 12
	s_cselect_b32 s91, s20, s13
	s_cselect_b32 s90, s33, s12
	v_add_u32_e32 v0, s29, v171
	s_cselect_b32 s89, s52, s79
	s_cselect_b32 s88, s53, s77
	s_add_i32 s12, 0, 0x14000
	ds_read_b128 v[174:177], v0
	ds_read_b128 v[196:199], v0 offset:1024
	ds_read_b128 v[200:203], v0 offset:2048
	ds_read_b128 v[204:207], v0 offset:3072
	v_add_u32_e32 v0, s12, v171
	ds_read_b128 v[208:211], v0
	ds_read_b128 v[212:215], v0 offset:1024
	ds_read_b128 v[216:219], v0 offset:2048
	ds_read_b128 v[220:223], v0 offset:3072
	v_lshl_add_u64 v[160:161], s[8:9], 0, v[138:139]
	s_add_i32 m0, s83, 0xc000
	ds_read_b128 v[224:227], v172
	ds_read_b128 v[228:231], v172 offset:1024
	ds_read_b128 v[232:235], v172 offset:2048
	ds_read_b128 v[236:239], v172 offset:3072
	ds_read_b128 v[240:243], v172 offset:4096
	ds_read_b128 v[244:247], v172 offset:5120
	ds_read_b128 v[248:251], v172 offset:6144
	ds_read_b128 v[188:191], v172 offset:7168
	global_load_lds_dwordx4 v[160:161], off
	v_lshl_add_u64 v[160:161], s[8:9], 0, v[140:141]
	s_add_i32 m0, s83, 0xe000
	s_nop 0
	global_load_lds_dwordx4 v[160:161], off
	s_waitcnt vmcnt(8)
	s_waitcnt lgkmcnt(0)
	s_barrier
	s_setprio 1
	s_waitcnt lgkmcnt(0)
	v_mfma_f32_16x16x32_bf16 v[126:129], v[174:177], v[224:227], v[126:129]
	v_mfma_f32_16x16x32_bf16 v[122:125], v[200:203], v[224:227], v[122:125]
	v_mfma_f32_16x16x32_bf16 v[118:121], v[174:177], v[232:235], v[118:121]
	v_mfma_f32_16x16x32_bf16 v[114:117], v[200:203], v[232:235], v[114:117]
	v_mfma_f32_16x16x32_bf16 v[102:105], v[174:177], v[240:243], v[102:105]
	v_mfma_f32_16x16x32_bf16 v[98:101], v[200:203], v[240:243], v[98:101]
	v_mfma_f32_16x16x32_bf16 v[86:89], v[174:177], v[248:251], v[86:89]
	v_mfma_f32_16x16x32_bf16 v[82:85], v[200:203], v[248:251], v[82:85]
	v_mfma_f32_16x16x32_bf16 v[126:129], v[196:199], v[228:231], v[126:129]
	v_mfma_f32_16x16x32_bf16 v[122:125], v[204:207], v[228:231], v[122:125]
	v_mfma_f32_16x16x32_bf16 v[118:121], v[196:199], v[236:239], v[118:121]
	v_mfma_f32_16x16x32_bf16 v[114:117], v[204:207], v[236:239], v[114:117]
	v_mfma_f32_16x16x32_bf16 v[102:105], v[196:199], v[244:247], v[102:105]
	v_mfma_f32_16x16x32_bf16 v[98:101], v[204:207], v[244:247], v[98:101]
	v_mfma_f32_16x16x32_bf16 v[86:89], v[196:199], v[188:191], v[86:89]
	v_mfma_f32_16x16x32_bf16 v[82:85], v[204:207], v[188:191], v[82:85]
	v_mfma_f32_16x16x32_bf16 v[110:113], v[208:211], v[224:227], v[110:113]
	v_mfma_f32_16x16x32_bf16 v[106:109], v[216:219], v[224:227], v[106:109]
	v_mfma_f32_16x16x32_bf16 v[94:97], v[208:211], v[232:235], v[94:97]
	v_mfma_f32_16x16x32_bf16 v[90:93], v[216:219], v[232:235], v[90:93]
	v_mfma_f32_16x16x32_bf16 v[78:81], v[208:211], v[240:243], v[78:81]
	v_mfma_f32_16x16x32_bf16 v[74:77], v[216:219], v[240:243], v[74:77]
	v_mfma_f32_16x16x32_bf16 v[70:73], v[208:211], v[248:251], v[70:73]
	v_mfma_f32_16x16x32_bf16 v[66:69], v[216:219], v[248:251], v[66:69]
	v_mfma_f32_16x16x32_bf16 v[110:113], v[212:215], v[228:231], v[110:113]
	v_mfma_f32_16x16x32_bf16 v[106:109], v[220:223], v[228:231], v[106:109]
	v_mfma_f32_16x16x32_bf16 v[94:97], v[212:215], v[236:239], v[94:97]
	v_mfma_f32_16x16x32_bf16 v[90:93], v[220:223], v[236:239], v[90:93]
	v_mfma_f32_16x16x32_bf16 v[78:81], v[212:215], v[244:247], v[78:81]
	v_mfma_f32_16x16x32_bf16 v[74:77], v[220:223], v[244:247], v[74:77]
	v_mfma_f32_16x16x32_bf16 v[70:73], v[212:215], v[188:191], v[70:73]
	v_mfma_f32_16x16x32_bf16 v[66:69], v[220:223], v[188:191], v[66:69]
	s_setprio 0
	s_barrier
	s_add_i32 s13, s29, s97
	v_lshl_add_u64 v[160:161], s[88:89], 0, v[132:133]
	s_mov_b32 m0, s13
	ds_read_b128 v[188:191], v172 offset:16384
	ds_read_b128 v[224:227], v172 offset:17408
	ds_read_b128 v[228:231], v172 offset:18432
	ds_read_b128 v[232:235], v172 offset:19456
	ds_read_b128 v[236:239], v172 offset:20480
	ds_read_b128 v[240:243], v172 offset:21504
	ds_read_b128 v[244:247], v172 offset:22528
	ds_read_b128 v[248:251], v172 offset:23552
	global_load_lds_dwordx4 v[160:161], off
	s_add_i32 m0, s13, 0x2000
	s_add_u32 s92, s88, 0x40000
	v_lshl_add_u64 v[166:167], s[88:89], 0, v[136:137]
	s_addc_u32 s93, s89, 0
	s_add_i32 s12, s12, s97
	global_load_lds_dwordx4 v[166:167], off
	v_lshl_add_u64 v[178:179], s[92:93], 0, v[132:133]
	s_mov_b32 m0, s12
	v_lshl_add_u64 v[252:253], s[90:91], 0, v[134:135]
	global_load_lds_dwordx4 v[178:179], off
	v_lshl_add_u64 v[178:179], s[92:93], 0, v[136:137]
	s_add_i32 m0, s12, 0x2000
	s_nop 0
	global_load_lds_dwordx4 v[178:179], off
	v_lshl_add_u64 v[178:179], s[90:91], 0, v[130:131]
	s_mov_b32 m0, s83
	s_nop 0
	global_load_lds_dwordx4 v[178:179], off
	s_mov_b32 m0, s45
	s_nop 0
	global_load_lds_dwordx4 v[252:253], off
	s_waitcnt vmcnt(8)
	s_waitcnt lgkmcnt(0)
	s_barrier
; #define PG8_STAGE(bufoff, gbase, voff) do { _Pragma("unroll") for (int _i = 0; _i < 2; ++_i) \
;         __builtin_amdgcn_global_load_lds((const unsigned*)((const char*)(gbase) + (voff)[_i]), (LAS unsigned*)(lds + (bufoff) + ldsw + _i * 8192), 16, 0, 0); } while (0)
; #define PG8_LDA(dst, b, h) do { _Pragma("unroll") for (int m = 0; m < 4; ++m) _Pragma("unroll") for (int k = 0; k < 2; ++k) dst[m][k] = *(const LAS bf16x8*)(lds + PG8_SA(b, h) + aoff + m * 2048 + k * 1024); } while (0)
; #define PG8_LDB(dst, b, h) do { _Pragma("unroll") for (int n = 0; n < 2; ++n) _Pragma("unroll") for (int k = 0; k < 2; ++k) dst[n][k] = *(const LAS bf16x8*)(lds + PG8_SB(b, h) + boff + n * 2048 + k * 1024); } while (0)
; #define PG8_MMA(ai, bj, At, Bt) do { __builtin_amdgcn_s_setprio(1); _Pragma("unroll") for (int m = 0; m < 4; ++m) _Pragma("unroll") for (int n = 0; n < 2; ++n) _Pragma("unroll") for (int k = 0; k < 2; ++k) \
;         acc[ai][bj][m][n] = __builtin_amdgcn_mfma_f32_16x16x32_bf16(Bt[n][k], At[m][k], acc[ai][bj][m][n], 0, 0, 0); __builtin_amdgcn_s_setprio(0); } while (0)
; #define PG8_WAIT_V(n) asm volatile("s_waitcnt vmcnt(" #n ")" ::: "memory")
; #define PG8_WAIT_L(n) asm volatile("s_waitcnt lgkmcnt(" #n ")" ::: "memory")
; #define PG8_BAR __builtin_amdgcn_s_barrier()
; #define PG8_SCHED __builtin_amdgcn_sched_barrier(0)
; template <class Epi>
; DI void gemm_phase(LAS unsigned char* lds, int tid, const Gemm g, const Order& S, const Epi& E) {
;     ...
;             PG8_WAIT_V(8); PG8_WAIT_L(0); PG8_BAR; PG8_MMA(1, 0, At, B0); PG8_MMA(1, 1, At, B1); PG8_BAR; PG8_SCHED;
;             PG8_LDB(B0, 1, 0); PG8_LDB(B1, 1, 1); PG8_SCHED; PG8_LDA(At, 1, 0); PG8_STAGE(PG8_SA(0, 1), a2 + hstepA, voffA);
;             PG8_WAIT_V(8); PG8_WAIT_L(0); PG8_BAR; PG8_MMA(0, 0, At, B0); PG8_MMA(0, 1, At, B1); PG8_BAR; PG8_SCHED;
	s_setprio 1
	s_waitcnt lgkmcnt(0)
	v_mfma_f32_16x16x32_bf16 v[62:65], v[174:177], v[188:191], v[62:65]
	v_mfma_f32_16x16x32_bf16 v[58:61], v[200:203], v[188:191], v[58:61]
	v_mfma_f32_16x16x32_bf16 v[54:57], v[174:177], v[228:231], v[54:57]
	v_mfma_f32_16x16x32_bf16 v[50:53], v[200:203], v[228:231], v[50:53]
	v_mfma_f32_16x16x32_bf16 v[38:41], v[174:177], v[236:239], v[38:41]
	v_mfma_f32_16x16x32_bf16 v[34:37], v[200:203], v[236:239], v[34:37]
	v_mfma_f32_16x16x32_bf16 v[22:25], v[174:177], v[244:247], v[22:25]
	v_mfma_f32_16x16x32_bf16 v[18:21], v[200:203], v[244:247], v[18:21]
	v_mfma_f32_16x16x32_bf16 v[62:65], v[196:199], v[224:227], v[62:65]
	v_mfma_f32_16x16x32_bf16 v[58:61], v[204:207], v[224:227], v[58:61]
	v_mfma_f32_16x16x32_bf16 v[54:57], v[196:199], v[232:235], v[54:57]
	v_mfma_f32_16x16x32_bf16 v[50:53], v[204:207], v[232:235], v[50:53]
	v_mfma_f32_16x16x32_bf16 v[38:41], v[196:199], v[240:243], v[38:41]
	v_mfma_f32_16x16x32_bf16 v[34:37], v[204:207], v[240:243], v[34:37]
	v_mfma_f32_16x16x32_bf16 v[22:25], v[196:199], v[248:251], v[22:25]
	v_mfma_f32_16x16x32_bf16 v[18:21], v[204:207], v[248:251], v[18:21]
	v_mfma_f32_16x16x32_bf16 v[46:49], v[208:211], v[188:191], v[46:49]
	v_mfma_f32_16x16x32_bf16 v[42:45], v[216:219], v[188:191], v[42:45]
	v_mfma_f32_16x16x32_bf16 v[30:33], v[208:211], v[228:231], v[30:33]
	v_mfma_f32_16x16x32_bf16 v[26:29], v[216:219], v[228:231], v[26:29]
	v_mfma_f32_16x16x32_bf16 v[14:17], v[208:211], v[236:239], v[14:17]
	v_mfma_f32_16x16x32_bf16 v[10:13], v[216:219], v[236:239], v[10:13]
	v_mfma_f32_16x16x32_bf16 v[6:9], v[208:211], v[244:247], v[6:9]
	v_mfma_f32_16x16x32_bf16 v[2:5], v[216:219], v[244:247], v[2:5]
	v_mfma_f32_16x16x32_bf16 v[46:49], v[212:215], v[224:227], v[46:49]
	v_mfma_f32_16x16x32_bf16 v[42:45], v[220:223], v[224:227], v[42:45]
	v_mfma_f32_16x16x32_bf16 v[30:33], v[212:215], v[232:235], v[30:33]
	v_mfma_f32_16x16x32_bf16 v[26:29], v[220:223], v[232:235], v[26:29]
	v_mfma_f32_16x16x32_bf16 v[14:17], v[212:215], v[240:243], v[14:17]
	v_mfma_f32_16x16x32_bf16 v[10:13], v[220:223], v[240:243], v[10:13]
	v_mfma_f32_16x16x32_bf16 v[6:9], v[212:215], v[248:251], v[6:9]
	v_mfma_f32_16x16x32_bf16 v[2:5], v[220:223], v[248:251], v[2:5]
	s_setprio 0
	s_barrier
	s_add_i32 s12, 0, 0x18000
	v_add_u32_e32 v0, s12, v171
	s_add_i32 s13, 0, 0x1c000
	ds_read_b128 v[174:177], v0
	ds_read_b128 v[188:191], v0 offset:1024
	ds_read_b128 v[196:199], v0 offset:2048
	ds_read_b128 v[200:203], v0 offset:3072
	v_add_u32_e32 v0, s13, v171
	ds_read_b128 v[204:207], v0
	ds_read_b128 v[208:211], v0 offset:1024
	ds_read_b128 v[212:215], v0 offset:2048
	ds_read_b128 v[216:219], v0 offset:3072
	s_add_u32 s90, s90, 0x40000
	s_addc_u32 s91, s91, 0
	s_mov_b32 m0, s34
	v_lshl_add_u64 v[184:185], s[90:91], 0, v[130:131]
	ds_read_b128 v[220:223], v172 offset:32768
	ds_read_b128 v[224:227], v172 offset:33792
	ds_read_b128 v[228:231], v172 offset:34816
	ds_read_b128 v[232:235], v172 offset:35840
	ds_read_b128 v[236:239], v172 offset:36864
	ds_read_b128 v[240:243], v172 offset:37888
	ds_read_b128 v[244:247], v172 offset:38912
	ds_read_b128 v[248:251], v172 offset:39936
	global_load_lds_dwordx4 v[184:185], off
	v_lshl_add_u64 v[184:185], s[90:91], 0, v[134:135]
	s_mov_b32 m0, s22
	s_nop 0
	global_load_lds_dwordx4 v[184:185], off
	s_waitcnt vmcnt(8)
	s_waitcnt lgkmcnt(0)
	s_barrier
	s_setprio 1
	s_waitcnt lgkmcnt(0)
	v_mfma_f32_16x16x32_bf16 v[126:129], v[174:177], v[220:223], v[126:129]
	v_mfma_f32_16x16x32_bf16 v[122:125], v[196:199], v[220:223], v[122:125]
	v_mfma_f32_16x16x32_bf16 v[118:121], v[174:177], v[228:231], v[118:121]
	v_mfma_f32_16x16x32_bf16 v[114:117], v[196:199], v[228:231], v[114:117]
	v_mfma_f32_16x16x32_bf16 v[102:105], v[174:177], v[236:239], v[102:105]
	v_mfma_f32_16x16x32_bf16 v[98:101], v[196:199], v[236:239], v[98:101]
	v_mfma_f32_16x16x32_bf16 v[86:89], v[174:177], v[244:247], v[86:89]
	v_mfma_f32_16x16x32_bf16 v[82:85], v[196:199], v[244:247], v[82:85]
	v_mfma_f32_16x16x32_bf16 v[126:129], v[188:191], v[224:227], v[126:129]
	v_mfma_f32_16x16x32_bf16 v[122:125], v[200:203], v[224:227], v[122:125]
	v_mfma_f32_16x16x32_bf16 v[118:121], v[188:191], v[232:235], v[118:121]
	v_mfma_f32_16x16x32_bf16 v[114:117], v[200:203], v[232:235], v[114:117]
	v_mfma_f32_16x16x32_bf16 v[102:105], v[188:191], v[240:243], v[102:105]
	v_mfma_f32_16x16x32_bf16 v[98:101], v[200:203], v[240:243], v[98:101]
	v_mfma_f32_16x16x32_bf16 v[86:89], v[188:191], v[248:251], v[86:89]
	v_mfma_f32_16x16x32_bf16 v[82:85], v[200:203], v[248:251], v[82:85]
	v_mfma_f32_16x16x32_bf16 v[110:113], v[204:207], v[220:223], v[110:113]
	v_mfma_f32_16x16x32_bf16 v[106:109], v[212:215], v[220:223], v[106:109]
	v_mfma_f32_16x16x32_bf16 v[94:97], v[204:207], v[228:231], v[94:97]
	v_mfma_f32_16x16x32_bf16 v[90:93], v[212:215], v[228:231], v[90:93]
	v_mfma_f32_16x16x32_bf16 v[78:81], v[204:207], v[236:239], v[78:81]
	v_mfma_f32_16x16x32_bf16 v[74:77], v[212:215], v[236:239], v[74:77]
	v_mfma_f32_16x16x32_bf16 v[70:73], v[204:207], v[244:247], v[70:73]
	v_mfma_f32_16x16x32_bf16 v[66:69], v[212:215], v[244:247], v[66:69]
	v_mfma_f32_16x16x32_bf16 v[110:113], v[208:211], v[224:227], v[110:113]
	v_mfma_f32_16x16x32_bf16 v[106:109], v[216:219], v[224:227], v[106:109]
	v_mfma_f32_16x16x32_bf16 v[94:97], v[208:211], v[232:235], v[94:97]
	v_mfma_f32_16x16x32_bf16 v[90:93], v[216:219], v[232:235], v[90:93]
	v_mfma_f32_16x16x32_bf16 v[78:81], v[208:211], v[240:243], v[78:81]
	v_mfma_f32_16x16x32_bf16 v[74:77], v[216:219], v[240:243], v[74:77]
	v_mfma_f32_16x16x32_bf16 v[70:73], v[208:211], v[248:251], v[70:73]
	v_mfma_f32_16x16x32_bf16 v[66:69], v[216:219], v[248:251], v[66:69]
	s_setprio 0
	s_barrier
; #define PG8_STAGE(bufoff, gbase, voff) do { _Pragma("unroll") for (int _i = 0; _i < 2; ++_i) \
;         __builtin_amdgcn_global_load_lds((const unsigned*)((const char*)(gbase) + (voff)[_i]), (LAS unsigned*)(lds + (bufoff) + ldsw + _i * 8192), 16, 0, 0); } while (0)
; #define PG8_LDA(dst, b, h) do { _Pragma("unroll") for (int m = 0; m < 4; ++m) _Pragma("unroll") for (int k = 0; k < 2; ++k) dst[m][k] = *(const LAS bf16x8*)(lds + PG8_SA(b, h) + aoff + m * 2048 + k * 1024); } while (0)
; #define PG8_MMA(ai, bj, At, Bt) do { __builtin_amdgcn_s_setprio(1); _Pragma("unroll") for (int m = 0; m < 4; ++m) _Pragma("unroll") for (int n = 0; n < 2; ++n) _Pragma("unroll") for (int k = 0; k < 2; ++k) \
;         acc[ai][bj][m][n] = __builtin_amdgcn_mfma_f32_16x16x32_bf16(Bt[n][k], At[m][k], acc[ai][bj][m][n], 0, 0, 0); __builtin_amdgcn_s_setprio(0); } while (0)
; #define PG8_WAIT_V(n) asm volatile("s_waitcnt vmcnt(" #n ")" ::: "memory")
; #define PG8_WAIT_L(n) asm volatile("s_waitcnt lgkmcnt(" #n ")" ::: "memory")
; #define PG8_BAR __builtin_amdgcn_s_barrier()
; #define PG8_SCHED __builtin_amdgcn_sched_barrier(0)
; template <class Epi>
; DI void gemm_phase(LAS unsigned char* lds, int tid, const Gemm g, const Order& S, const Epi& E) {
;     ...
;             PG8_LDA(At, 1, 1); PG8_STAGE(PG8_SB(1, 0), b3, voffB); PG8_STAGE(PG8_SB(1, 1), b3 + hstepB, voffB); PG8_STAGE(PG8_SA(1, 0), a3, voffA);
;             PG8_WAIT_V(8); PG8_WAIT_L(0); PG8_BAR; PG8_MMA(1, 0, At, B0); PG8_MMA(1, 1, At, B1); PG8_BAR; PG8_SCHED;
;         }
;         if (wr == 0) PG8_BAR;
	s_add_i32 s12, s12, s97
	v_lshl_add_u64 v[160:161], v[160:161], 0, s[24:25]
	s_mov_b32 m0, s12
	ds_read_b128 v[220:223], v172 offset:49152
	ds_read_b128 v[224:227], v172 offset:50176
	ds_read_b128 v[228:231], v172 offset:51200
	ds_read_b128 v[232:235], v172 offset:52224
	ds_read_b128 v[236:239], v172 offset:53248
	ds_read_b128 v[240:243], v172 offset:54272
	ds_read_b128 v[244:247], v172 offset:55296
	ds_read_b128 v[248:251], v172 offset:56320
	global_load_lds_dwordx4 v[160:161], off
	s_add_i32 m0, s12, 0x2000
	s_add_u32 s88, s88, 0x40080
	v_lshl_add_u64 v[160:161], v[166:167], 0, s[24:25]
	s_addc_u32 s89, s89, 0
	s_add_i32 s12, s13, s97
	global_load_lds_dwordx4 v[160:161], off
	v_lshl_add_u64 v[160:161], s[88:89], 0, v[132:133]
	s_mov_b32 m0, s12
	s_nop 0
	global_load_lds_dwordx4 v[160:161], off
	v_lshl_add_u64 v[160:161], s[88:89], 0, v[136:137]
	s_add_i32 m0, s12, 0x2000
	s_nop 0
	global_load_lds_dwordx4 v[160:161], off
	v_lshl_add_u64 v[160:161], v[178:179], 0, s[24:25]
	s_mov_b32 m0, s48
	s_nop 0
	global_load_lds_dwordx4 v[160:161], off
	v_lshl_add_u64 v[160:161], v[252:253], 0, s[24:25]
	s_mov_b32 m0, s40
	s_nop 0
	global_load_lds_dwordx4 v[160:161], off
	s_waitcnt vmcnt(8)
	s_waitcnt lgkmcnt(0)
	s_barrier
	s_setprio 1
	s_waitcnt lgkmcnt(0)
	v_mfma_f32_16x16x32_bf16 v[62:65], v[174:177], v[220:223], v[62:65]
	v_mfma_f32_16x16x32_bf16 v[58:61], v[196:199], v[220:223], v[58:61]
	v_mfma_f32_16x16x32_bf16 v[54:57], v[174:177], v[228:231], v[54:57]
	v_mfma_f32_16x16x32_bf16 v[50:53], v[196:199], v[228:231], v[50:53]
	v_mfma_f32_16x16x32_bf16 v[38:41], v[174:177], v[236:239], v[38:41]
	v_mfma_f32_16x16x32_bf16 v[34:37], v[196:199], v[236:239], v[34:37]
	v_mfma_f32_16x16x32_bf16 v[22:25], v[174:177], v[244:247], v[22:25]
	v_mfma_f32_16x16x32_bf16 v[18:21], v[196:199], v[244:247], v[18:21]
	v_mfma_f32_16x16x32_bf16 v[62:65], v[188:191], v[224:227], v[62:65]
	v_mfma_f32_16x16x32_bf16 v[58:61], v[200:203], v[224:227], v[58:61]
	v_mfma_f32_16x16x32_bf16 v[54:57], v[188:191], v[232:235], v[54:57]
	v_mfma_f32_16x16x32_bf16 v[50:53], v[200:203], v[232:235], v[50:53]
	v_mfma_f32_16x16x32_bf16 v[38:41], v[188:191], v[240:243], v[38:41]
	v_mfma_f32_16x16x32_bf16 v[34:37], v[200:203], v[240:243], v[34:37]
	v_mfma_f32_16x16x32_bf16 v[22:25], v[188:191], v[248:251], v[22:25]
	v_mfma_f32_16x16x32_bf16 v[18:21], v[200:203], v[248:251], v[18:21]
	v_mfma_f32_16x16x32_bf16 v[46:49], v[204:207], v[220:223], v[46:49]
	v_mfma_f32_16x16x32_bf16 v[42:45], v[212:215], v[220:223], v[42:45]
	v_mfma_f32_16x16x32_bf16 v[30:33], v[204:207], v[228:231], v[30:33]
	v_mfma_f32_16x16x32_bf16 v[26:29], v[212:215], v[228:231], v[26:29]
	v_mfma_f32_16x16x32_bf16 v[14:17], v[204:207], v[236:239], v[14:17]
	v_mfma_f32_16x16x32_bf16 v[10:13], v[212:215], v[236:239], v[10:13]
	v_mfma_f32_16x16x32_bf16 v[6:9], v[204:207], v[244:247], v[6:9]
	v_mfma_f32_16x16x32_bf16 v[2:5], v[212:215], v[244:247], v[2:5]
	v_mfma_f32_16x16x32_bf16 v[46:49], v[208:211], v[224:227], v[46:49]
	v_mfma_f32_16x16x32_bf16 v[42:45], v[216:219], v[224:227], v[42:45]
	v_mfma_f32_16x16x32_bf16 v[30:33], v[208:211], v[232:235], v[30:33]
	v_mfma_f32_16x16x32_bf16 v[26:29], v[216:219], v[232:235], v[26:29]
	v_mfma_f32_16x16x32_bf16 v[14:17], v[208:211], v[240:243], v[14:17]
	v_mfma_f32_16x16x32_bf16 v[10:13], v[216:219], v[240:243], v[10:13]
	v_mfma_f32_16x16x32_bf16 v[6:9], v[208:211], v[248:251], v[6:9]
	v_mfma_f32_16x16x32_bf16 v[2:5], v[216:219], v[248:251], v[2:5]
	s_setprio 0
	s_barrier
	s_add_i32 s81, s81, 2
	s_add_u32 s8, s8, 0x100
	s_addc_u32 s9, s9, 0
	s_add_u32 s77, s77, 0x100
	s_addc_u32 s79, s79, 0
	s_cmp_gt_u32 s81, 13
	s_cbranch_scc0 .LBB0_387
	s_and_b64 vcc, exec, s[74:75]
	s_cbranch_vccz .LBB0_390
	s_barrier

; DI const char* a_of(const Gemm& g, const Unit& u) { return (const char*)(g.A + (size_t)u.pz * g.zA + (size_t)u.pm * BM * g.lda); }
; DI const char* b_of(const Gemm& g, const Unit& u) { return (const char*)(g.Bt + (size_t)u.pz * g.zB + (size_t)u.pn * BM * g.ldb); }
; #define PG8_STAGE(bufoff, gbase, voff) do { _Pragma("unroll") for (int _i = 0; _i < 2; ++_i) \
;         __builtin_amdgcn_global_load_lds((const unsigned*)((const char*)(gbase) + (voff)[_i]), (LAS unsigned*)(lds + (bufoff) + ldsw + _i * 8192), 16, 0, 0); } while (0)
; #define PG8_LDA(dst, b, h) do { _Pragma("unroll") for (int m = 0; m < 4; ++m) _Pragma("unroll") for (int k = 0; k < 2; ++k) dst[m][k] = *(const LAS bf16x8*)(lds + PG8_SA(b, h) + aoff + m * 2048 + k * 1024); } while (0)
; #define PG8_LDB(dst, b, h) do { _Pragma("unroll") for (int n = 0; n < 2; ++n) _Pragma("unroll") for (int k = 0; k < 2; ++k) dst[n][k] = *(const LAS bf16x8*)(lds + PG8_SB(b, h) + boff + n * 2048 + k * 1024); } while (0)
; #define PG8_WAIT_V(n) asm volatile("s_waitcnt vmcnt(" #n ")" ::: "memory")
; #define PG8_WAIT_L(n) asm volatile("s_waitcnt lgkmcnt(" #n ")" ::: "memory")
; #define PG8_BAR __builtin_amdgcn_s_barrier()
; template <class Epi>
; DI void gemm_phase(LAS unsigned char* lds, int tid, const Gemm g, const Order& S, const Epi& E) {
;     ...
;         const bool has_next = S.next(ui + 1, nxt);
;         const char* nA = has_next ? a_of(g, nxt) : cA; const char* nB = has_next ? b_of(g, nxt) : cB;
; #pragma unroll 1
;         for (int t = 0; t < nt; t += 2) {
;             const bool last = (t == nt - 2);
;             const char* a1 = cA + (size_t)(t + 1) * kstep;
;             const char* a2 = last ? nA : cA + (size_t)(t + 2) * kstep; const char* b2 = last ? nB : cB + (size_t)(t + 2) * kstep;
;             const char* a3 = a2 + kstep; const char* b3 = b2 + kstep;
;             PG8_LDB(B0, 0, 0); PG8_LDB(B1, 0, 1); PG8_SCHED; PG8_LDA(At, 0, 0); PG8_STAGE(PG8_SA(1, 1), a1 + hstepA, voffA);
;             PG8_WAIT_V(8); PG8_WAIT_L(0); PG8_BAR; PG8_MMA(0, 0, At, B0); PG8_MMA(0, 1, At, B1); PG8_BAR; PG8_SCHED;
;             PG8_LDA(At, 0, 1); PG8_STAGE(PG8_SB(0, 0), b2, voffB); PG8_STAGE(PG8_SB(0, 1), b2 + hstepB, voffB); PG8_STAGE(PG8_SA(0, 0), a2, voffA);
;             PG8_WAIT_V(8); PG8_WAIT_L(0); PG8_BAR; PG8_MMA(1, 0, At, B0); PG8_MMA(1, 1, At, B1); PG8_BAR; PG8_SCHED;
.LBB0_466:
	s_add_i32 vcc_hi, s92, 2
	s_add_u32 s94, s90, 0x80
	s_addc_u32 s93, s91, 0
	s_add_i32 s29, 0, 0x10000
	s_cmp_eq_u32 s45, s92
	s_cselect_b32 s93, s7, s93
	s_cselect_b32 s92, s6, s94
	v_add_u32_e32 v140, s29, v143
	s_cselect_b32 s95, s89, vcc_lo
	s_cselect_b32 s94, s88, s53
	s_add_i32 s12, 0, 0x14000
	ds_read_b128 v[146:149], v140
	ds_read_b128 v[150:153], v140 offset:1024
	ds_read_b128 v[154:157], v140 offset:2048
	ds_read_b128 v[158:161], v140 offset:3072
	v_add_u32_e32 v140, s12, v143
	ds_read_b128 v[170:173], v140
	ds_read_b128 v[174:177], v140 offset:1024
	ds_read_b128 v[196:199], v140 offset:2048
	ds_read_b128 v[200:203], v140 offset:3072
	v_lshl_add_u64 v[140:141], s[90:91], 0, v[136:137]
	s_add_i32 m0, s22, 0xc000
	ds_read_b128 v[204:207], v145
	ds_read_b128 v[208:211], v145 offset:1024
	ds_read_b128 v[212:215], v145 offset:2048
	ds_read_b128 v[216:219], v145 offset:3072
	ds_read_b128 v[220:223], v145 offset:4096
	ds_read_b128 v[224:227], v145 offset:5120
	ds_read_b128 v[228:231], v145 offset:6144
	ds_read_b128 v[232:235], v145 offset:7168
	global_load_lds_dwordx4 v[140:141], off
	v_lshl_add_u64 v[140:141], s[90:91], 0, v[138:139]
	s_add_i32 m0, s22, 0xe000
	s_nop 0
	global_load_lds_dwordx4 v[140:141], off
	s_waitcnt vmcnt(8)
	s_waitcnt lgkmcnt(0)
	s_barrier
	s_setprio 1
	s_waitcnt lgkmcnt(0)
	v_mfma_f32_16x16x32_bf16 v[126:129], v[146:149], v[204:207], v[126:129]
	v_mfma_f32_16x16x32_bf16 v[122:125], v[154:157], v[204:207], v[122:125]
	v_mfma_f32_16x16x32_bf16 v[118:121], v[146:149], v[212:215], v[118:121]
	v_mfma_f32_16x16x32_bf16 v[110:113], v[154:157], v[212:215], v[110:113]
	v_mfma_f32_16x16x32_bf16 v[102:105], v[146:149], v[220:223], v[102:105]
	v_mfma_f32_16x16x32_bf16 v[94:97], v[154:157], v[220:223], v[94:97]
	v_mfma_f32_16x16x32_bf16 v[86:89], v[146:149], v[228:231], v[86:89]
	v_mfma_f32_16x16x32_bf16 v[78:81], v[154:157], v[228:231], v[78:81]
	v_mfma_f32_16x16x32_bf16 v[126:129], v[150:153], v[208:211], v[126:129]
	v_mfma_f32_16x16x32_bf16 v[122:125], v[158:161], v[208:211], v[122:125]
	v_mfma_f32_16x16x32_bf16 v[118:121], v[150:153], v[216:219], v[118:121]
	v_mfma_f32_16x16x32_bf16 v[110:113], v[158:161], v[216:219], v[110:113]
	v_mfma_f32_16x16x32_bf16 v[102:105], v[150:153], v[224:227], v[102:105]
	v_mfma_f32_16x16x32_bf16 v[94:97], v[158:161], v[224:227], v[94:97]
	v_mfma_f32_16x16x32_bf16 v[86:89], v[150:153], v[232:235], v[86:89]
	v_mfma_f32_16x16x32_bf16 v[78:81], v[158:161], v[232:235], v[78:81]
	v_mfma_f32_16x16x32_bf16 v[114:117], v[170:173], v[204:207], v[114:117]
	v_mfma_f32_16x16x32_bf16 v[106:109], v[196:199], v[204:207], v[106:109]
	v_mfma_f32_16x16x32_bf16 v[98:101], v[170:173], v[212:215], v[98:101]
	v_mfma_f32_16x16x32_bf16 v[90:93], v[196:199], v[212:215], v[90:93]
	v_mfma_f32_16x16x32_bf16 v[82:85], v[170:173], v[220:223], v[82:85]
	v_mfma_f32_16x16x32_bf16 v[74:77], v[196:199], v[220:223], v[74:77]
	v_mfma_f32_16x16x32_bf16 v[70:73], v[170:173], v[228:231], v[70:73]
	v_mfma_f32_16x16x32_bf16 v[66:69], v[196:199], v[228:231], v[66:69]
	v_mfma_f32_16x16x32_bf16 v[114:117], v[174:177], v[208:211], v[114:117]
	v_mfma_f32_16x16x32_bf16 v[106:109], v[200:203], v[208:211], v[106:109]
	v_mfma_f32_16x16x32_bf16 v[98:101], v[174:177], v[216:219], v[98:101]
	v_mfma_f32_16x16x32_bf16 v[90:93], v[200:203], v[216:219], v[90:93]
	v_mfma_f32_16x16x32_bf16 v[82:85], v[174:177], v[224:227], v[82:85]
	v_mfma_f32_16x16x32_bf16 v[74:77], v[200:203], v[224:227], v[74:77]
	v_mfma_f32_16x16x32_bf16 v[70:73], v[174:177], v[232:235], v[70:73]
	v_mfma_f32_16x16x32_bf16 v[66:69], v[200:203], v[232:235], v[66:69]
	s_setprio 0
	s_barrier
	s_add_i32 s13, s29, s17
	v_lshl_add_u64 v[140:141], s[94:95], 0, v[0:1]
	s_mov_b32 m0, s13
	ds_read_b128 v[204:207], v145 offset:16384
	ds_read_b128 v[208:211], v145 offset:17408
	ds_read_b128 v[212:215], v145 offset:18432
	ds_read_b128 v[216:219], v145 offset:19456
	ds_read_b128 v[220:223], v145 offset:20480
	ds_read_b128 v[224:227], v145 offset:21504
	ds_read_b128 v[228:231], v145 offset:22528
	ds_read_b128 v[232:235], v145 offset:23552
	global_load_lds_dwordx4 v[140:141], off
	s_add_i32 m0, s13, 0x2000
	v_lshl_add_u64 v[166:167], s[94:95], 0, v[130:131]
	s_add_u32 s94, s94, s20
	s_addc_u32 s95, s95, 0
	s_add_i32 s12, s12, s17
	global_load_lds_dwordx4 v[166:167], off
	v_lshl_add_u64 v[178:179], s[94:95], 0, v[0:1]
	s_mov_b32 m0, s12
	v_lshl_add_u64 v[188:189], s[94:95], 0, v[130:131]
	global_load_lds_dwordx4 v[178:179], off
	s_add_i32 m0, s12, 0x2000
	v_lshl_add_u64 v[190:191], s[92:93], 0, v[134:135]
	global_load_lds_dwordx4 v[188:189], off
	s_mov_b32 m0, s22
	v_lshl_add_u64 v[236:237], s[92:93], 0, v[132:133]
	global_load_lds_dwordx4 v[190:191], off
	s_mov_b32 m0, s26
	s_nop 0
	global_load_lds_dwordx4 v[236:237], off
	s_waitcnt vmcnt(8)
	s_waitcnt lgkmcnt(0)
	s_barrier
; #define PG8_STAGE(bufoff, gbase, voff) do { _Pragma("unroll") for (int _i = 0; _i < 2; ++_i) \
;         __builtin_amdgcn_global_load_lds((const unsigned*)((const char*)(gbase) + (voff)[_i]), (LAS unsigned*)(lds + (bufoff) + ldsw + _i * 8192), 16, 0, 0); } while (0)
; #define PG8_LDA(dst, b, h) do { _Pragma("unroll") for (int m = 0; m < 4; ++m) _Pragma("unroll") for (int k = 0; k < 2; ++k) dst[m][k] = *(const LAS bf16x8*)(lds + PG8_SA(b, h) + aoff + m * 2048 + k * 1024); } while (0)
; #define PG8_LDB(dst, b, h) do { _Pragma("unroll") for (int n = 0; n < 2; ++n) _Pragma("unroll") for (int k = 0; k < 2; ++k) dst[n][k] = *(const LAS bf16x8*)(lds + PG8_SB(b, h) + boff + n * 2048 + k * 1024); } while (0)
; #define PG8_MMA(ai, bj, At, Bt) do { __builtin_amdgcn_s_setprio(1); _Pragma("unroll") for (int m = 0; m < 4; ++m) _Pragma("unroll") for (int n = 0; n < 2; ++n) _Pragma("unroll") for (int k = 0; k < 2; ++k) \
;         acc[ai][bj][m][n] = __builtin_amdgcn_mfma_f32_16x16x32_bf16(Bt[n][k], At[m][k], acc[ai][bj][m][n], 0, 0, 0); __builtin_amdgcn_s_setprio(0); } while (0)
; #define PG8_WAIT_V(n) asm volatile("s_waitcnt vmcnt(" #n ")" ::: "memory")
; #define PG8_WAIT_L(n) asm volatile("s_waitcnt lgkmcnt(" #n ")" ::: "memory")
; #define PG8_BAR __builtin_amdgcn_s_barrier()
; #define PG8_SCHED __builtin_amdgcn_sched_barrier(0)
; template <class Epi>
; DI void gemm_phase(LAS unsigned char* lds, int tid, const Gemm g, const Order& S, const Epi& E) {
;     ...
;             PG8_WAIT_V(8); PG8_WAIT_L(0); PG8_BAR; PG8_MMA(1, 0, At, B0); PG8_MMA(1, 1, At, B1); PG8_BAR; PG8_SCHED;
;             PG8_LDB(B0, 1, 0); PG8_LDB(B1, 1, 1); PG8_SCHED; PG8_LDA(At, 1, 0); PG8_STAGE(PG8_SA(0, 1), a2 + hstepA, voffA);
;             PG8_WAIT_V(8); PG8_WAIT_L(0); PG8_BAR; PG8_MMA(0, 0, At, B0); PG8_MMA(0, 1, At, B1); PG8_BAR; PG8_SCHED;
	s_setprio 1
	s_waitcnt lgkmcnt(0)
	v_mfma_f32_16x16x32_bf16 v[62:65], v[146:149], v[204:207], v[62:65]
	v_mfma_f32_16x16x32_bf16 v[58:61], v[154:157], v[204:207], v[58:61]
	v_mfma_f32_16x16x32_bf16 v[54:57], v[146:149], v[212:215], v[54:57]
	v_mfma_f32_16x16x32_bf16 v[46:49], v[154:157], v[212:215], v[46:49]
	v_mfma_f32_16x16x32_bf16 v[38:41], v[146:149], v[220:223], v[38:41]
	v_mfma_f32_16x16x32_bf16 v[30:33], v[154:157], v[220:223], v[30:33]
	v_mfma_f32_16x16x32_bf16 v[22:25], v[146:149], v[228:231], v[22:25]
	v_mfma_f32_16x16x32_bf16 v[14:17], v[154:157], v[228:231], v[14:17]
	v_mfma_f32_16x16x32_bf16 v[62:65], v[150:153], v[208:211], v[62:65]
	v_mfma_f32_16x16x32_bf16 v[58:61], v[158:161], v[208:211], v[58:61]
	v_mfma_f32_16x16x32_bf16 v[54:57], v[150:153], v[216:219], v[54:57]
	v_mfma_f32_16x16x32_bf16 v[46:49], v[158:161], v[216:219], v[46:49]
	v_mfma_f32_16x16x32_bf16 v[38:41], v[150:153], v[224:227], v[38:41]
	v_mfma_f32_16x16x32_bf16 v[30:33], v[158:161], v[224:227], v[30:33]
	v_mfma_f32_16x16x32_bf16 v[22:25], v[150:153], v[232:235], v[22:25]
	v_mfma_f32_16x16x32_bf16 v[14:17], v[158:161], v[232:235], v[14:17]
	v_mfma_f32_16x16x32_bf16 v[50:53], v[170:173], v[204:207], v[50:53]
	v_mfma_f32_16x16x32_bf16 v[42:45], v[196:199], v[204:207], v[42:45]
	v_mfma_f32_16x16x32_bf16 v[34:37], v[170:173], v[212:215], v[34:37]
	v_mfma_f32_16x16x32_bf16 v[26:29], v[196:199], v[212:215], v[26:29]
	v_mfma_f32_16x16x32_bf16 v[18:21], v[170:173], v[220:223], v[18:21]
	v_mfma_f32_16x16x32_bf16 v[10:13], v[196:199], v[220:223], v[10:13]
	v_mfma_f32_16x16x32_bf16 v[6:9], v[170:173], v[228:231], v[6:9]
	v_mfma_f32_16x16x32_bf16 v[2:5], v[196:199], v[228:231], v[2:5]
	v_mfma_f32_16x16x32_bf16 v[50:53], v[174:177], v[208:211], v[50:53]
	v_mfma_f32_16x16x32_bf16 v[42:45], v[200:203], v[208:211], v[42:45]
	v_mfma_f32_16x16x32_bf16 v[34:37], v[174:177], v[216:219], v[34:37]
	v_mfma_f32_16x16x32_bf16 v[26:29], v[200:203], v[216:219], v[26:29]
	v_mfma_f32_16x16x32_bf16 v[18:21], v[174:177], v[224:227], v[18:21]
	v_mfma_f32_16x16x32_bf16 v[10:13], v[200:203], v[224:227], v[10:13]
	v_mfma_f32_16x16x32_bf16 v[6:9], v[174:177], v[232:235], v[6:9]
	v_mfma_f32_16x16x32_bf16 v[2:5], v[200:203], v[232:235], v[2:5]
	s_setprio 0
	s_barrier
	s_add_i32 s12, 0, 0x18000
	s_add_i32 s13, 0, 0x1c000
	v_add_u32_e32 v158, s12, v143
	v_add_u32_e32 v165, s13, v143
	ds_read_b128 v[146:149], v158
	ds_read_b128 v[150:153], v158 offset:1024
	ds_read_b128 v[154:157], v158 offset:2048
	ds_read_b128 v[158:161], v158 offset:3072
	ds_read_b128 v[170:173], v165
	ds_read_b128 v[174:177], v165 offset:1024
	ds_read_b128 v[196:199], v165 offset:2048
	ds_read_b128 v[200:203], v165 offset:3072
	s_add_u32 s92, s92, s20
	s_addc_u32 s93, s93, 0
	s_mov_b32 m0, s30
	v_lshl_add_u64 v[238:239], s[92:93], 0, v[134:135]
	ds_read_b128 v[204:207], v145 offset:32768
	ds_read_b128 v[208:211], v145 offset:33792
	ds_read_b128 v[212:215], v145 offset:34816
	ds_read_b128 v[216:219], v145 offset:35840
	ds_read_b128 v[220:223], v145 offset:36864
	ds_read_b128 v[224:227], v145 offset:37888
	ds_read_b128 v[228:231], v145 offset:38912
	ds_read_b128 v[232:235], v145 offset:39936
	global_load_lds_dwordx4 v[238:239], off
	v_lshl_add_u64 v[238:239], s[92:93], 0, v[132:133]
	s_mov_b32 m0, s31
	s_nop 0
	global_load_lds_dwordx4 v[238:239], off
	s_waitcnt vmcnt(8)
	s_waitcnt lgkmcnt(0)
	s_barrier
	s_setprio 1
	s_waitcnt lgkmcnt(0)
	v_mfma_f32_16x16x32_bf16 v[126:129], v[146:149], v[204:207], v[126:129]
	v_mfma_f32_16x16x32_bf16 v[122:125], v[154:157], v[204:207], v[122:125]
	v_mfma_f32_16x16x32_bf16 v[118:121], v[146:149], v[212:215], v[118:121]
	v_mfma_f32_16x16x32_bf16 v[110:113], v[154:157], v[212:215], v[110:113]
	v_mfma_f32_16x16x32_bf16 v[102:105], v[146:149], v[220:223], v[102:105]
	v_mfma_f32_16x16x32_bf16 v[94:97], v[154:157], v[220:223], v[94:97]
	v_mfma_f32_16x16x32_bf16 v[86:89], v[146:149], v[228:231], v[86:89]
	v_mfma_f32_16x16x32_bf16 v[78:81], v[154:157], v[228:231], v[78:81]
	v_mfma_f32_16x16x32_bf16 v[126:129], v[150:153], v[208:211], v[126:129]
	v_mfma_f32_16x16x32_bf16 v[122:125], v[158:161], v[208:211], v[122:125]
	v_mfma_f32_16x16x32_bf16 v[118:121], v[150:153], v[216:219], v[118:121]
	v_mfma_f32_16x16x32_bf16 v[110:113], v[158:161], v[216:219], v[110:113]
	v_mfma_f32_16x16x32_bf16 v[102:105], v[150:153], v[224:227], v[102:105]
	v_mfma_f32_16x16x32_bf16 v[94:97], v[158:161], v[224:227], v[94:97]
	v_mfma_f32_16x16x32_bf16 v[86:89], v[150:153], v[232:235], v[86:89]
	v_mfma_f32_16x16x32_bf16 v[78:81], v[158:161], v[232:235], v[78:81]
	v_mfma_f32_16x16x32_bf16 v[114:117], v[170:173], v[204:207], v[114:117]
	v_mfma_f32_16x16x32_bf16 v[106:109], v[196:199], v[204:207], v[106:109]
	v_mfma_f32_16x16x32_bf16 v[98:101], v[170:173], v[212:215], v[98:101]
	v_mfma_f32_16x16x32_bf16 v[90:93], v[196:199], v[212:215], v[90:93]
	v_mfma_f32_16x16x32_bf16 v[82:85], v[170:173], v[220:223], v[82:85]
	v_mfma_f32_16x16x32_bf16 v[74:77], v[196:199], v[220:223], v[74:77]
	v_mfma_f32_16x16x32_bf16 v[70:73], v[170:173], v[228:231], v[70:73]
	v_mfma_f32_16x16x32_bf16 v[66:69], v[196:199], v[228:231], v[66:69]
	v_mfma_f32_16x16x32_bf16 v[114:117], v[174:177], v[208:211], v[114:117]
	v_mfma_f32_16x16x32_bf16 v[106:109], v[200:203], v[208:211], v[106:109]
	v_mfma_f32_16x16x32_bf16 v[98:101], v[174:177], v[216:219], v[98:101]
	v_mfma_f32_16x16x32_bf16 v[90:93], v[200:203], v[216:219], v[90:93]
	v_mfma_f32_16x16x32_bf16 v[82:85], v[174:177], v[224:227], v[82:85]
	v_mfma_f32_16x16x32_bf16 v[74:77], v[200:203], v[224:227], v[74:77]
	v_mfma_f32_16x16x32_bf16 v[70:73], v[174:177], v[232:235], v[70:73]
	v_mfma_f32_16x16x32_bf16 v[66:69], v[200:203], v[232:235], v[66:69]
	s_setprio 0
	s_barrier
; #define PG8_STAGE(bufoff, gbase, voff) do { _Pragma("unroll") for (int _i = 0; _i < 2; ++_i) \
;         __builtin_amdgcn_global_load_lds((const unsigned*)((const char*)(gbase) + (voff)[_i]), (LAS unsigned*)(lds + (bufoff) + ldsw + _i * 8192), 16, 0, 0); } while (0)
; #define PG8_LDA(dst, b, h) do { _Pragma("unroll") for (int m = 0; m < 4; ++m) _Pragma("unroll") for (int k = 0; k < 2; ++k) dst[m][k] = *(const LAS bf16x8*)(lds + PG8_SA(b, h) + aoff + m * 2048 + k * 1024); } while (0)
; #define PG8_MMA(ai, bj, At, Bt) do { __builtin_amdgcn_s_setprio(1); _Pragma("unroll") for (int m = 0; m < 4; ++m) _Pragma("unroll") for (int n = 0; n < 2; ++n) _Pragma("unroll") for (int k = 0; k < 2; ++k) \
;         acc[ai][bj][m][n] = __builtin_amdgcn_mfma_f32_16x16x32_bf16(Bt[n][k], At[m][k], acc[ai][bj][m][n], 0, 0, 0); __builtin_amdgcn_s_setprio(0); } while (0)
; #define PG8_WAIT_V(n) asm volatile("s_waitcnt vmcnt(" #n ")" ::: "memory")
; #define PG8_WAIT_L(n) asm volatile("s_waitcnt lgkmcnt(" #n ")" ::: "memory")
; #define PG8_BAR __builtin_amdgcn_s_barrier()
; #define PG8_SCHED __builtin_amdgcn_sched_barrier(0)
; template <class Epi>
; DI void gemm_phase(LAS unsigned char* lds, int tid, const Gemm g, const Order& S, const Epi& E) {
;     ...
;             PG8_LDA(At, 1, 1); PG8_STAGE(PG8_SB(1, 0), b3, voffB); PG8_STAGE(PG8_SB(1, 1), b3 + hstepB, voffB); PG8_STAGE(PG8_SA(1, 0), a3, voffA);
;             PG8_WAIT_V(8); PG8_WAIT_L(0); PG8_BAR; PG8_MMA(1, 0, At, B0); PG8_MMA(1, 1, At, B1); PG8_BAR; PG8_SCHED;
;         }
;         if (wr == 0) PG8_BAR;
	s_add_i32 s12, s12, s17
	v_lshl_add_u64 v[140:141], v[140:141], 0, s[24:25]
	s_mov_b32 m0, s12
	ds_read_b128 v[204:207], v145 offset:49152
	ds_read_b128 v[208:211], v145 offset:50176
	ds_read_b128 v[212:215], v145 offset:51200
	ds_read_b128 v[216:219], v145 offset:52224
	ds_read_b128 v[220:223], v145 offset:53248
	ds_read_b128 v[224:227], v145 offset:54272
	ds_read_b128 v[228:231], v145 offset:55296
	ds_read_b128 v[232:235], v145 offset:56320
	global_load_lds_dwordx4 v[140:141], off
	v_lshl_add_u64 v[140:141], v[166:167], 0, s[24:25]
	s_add_i32 m0, s12, 0x2000
	s_add_i32 s12, s13, s17
	global_load_lds_dwordx4 v[140:141], off
	v_lshl_add_u64 v[140:141], v[178:179], 0, s[24:25]
	s_mov_b32 m0, s12
	s_nop 0
	global_load_lds_dwordx4 v[140:141], off
	v_lshl_add_u64 v[140:141], v[188:189], 0, s[24:25]
	s_add_i32 m0, s12, 0x2000
	s_nop 0
	global_load_lds_dwordx4 v[140:141], off
	v_lshl_add_u64 v[140:141], v[190:191], 0, s[24:25]
	s_mov_b32 m0, s40
	s_nop 0
	global_load_lds_dwordx4 v[140:141], off
	v_lshl_add_u64 v[140:141], v[236:237], 0, s[24:25]
	s_mov_b32 m0, s41
	s_nop 0
	global_load_lds_dwordx4 v[140:141], off
	s_waitcnt vmcnt(8)
	s_waitcnt lgkmcnt(0)
	s_barrier
	s_setprio 1
	s_waitcnt lgkmcnt(0)
	v_mfma_f32_16x16x32_bf16 v[62:65], v[146:149], v[204:207], v[62:65]
	v_mfma_f32_16x16x32_bf16 v[58:61], v[154:157], v[204:207], v[58:61]
	v_mfma_f32_16x16x32_bf16 v[54:57], v[146:149], v[212:215], v[54:57]
	v_mfma_f32_16x16x32_bf16 v[46:49], v[154:157], v[212:215], v[46:49]
	v_mfma_f32_16x16x32_bf16 v[38:41], v[146:149], v[220:223], v[38:41]
	v_mfma_f32_16x16x32_bf16 v[30:33], v[154:157], v[220:223], v[30:33]
	v_mfma_f32_16x16x32_bf16 v[22:25], v[146:149], v[228:231], v[22:25]
	v_mfma_f32_16x16x32_bf16 v[14:17], v[154:157], v[228:231], v[14:17]
	v_mfma_f32_16x16x32_bf16 v[62:65], v[150:153], v[208:211], v[62:65]
	v_mfma_f32_16x16x32_bf16 v[58:61], v[158:161], v[208:211], v[58:61]
	v_mfma_f32_16x16x32_bf16 v[54:57], v[150:153], v[216:219], v[54:57]
	v_mfma_f32_16x16x32_bf16 v[46:49], v[158:161], v[216:219], v[46:49]
	v_mfma_f32_16x16x32_bf16 v[38:41], v[150:153], v[224:227], v[38:41]
	v_mfma_f32_16x16x32_bf16 v[30:33], v[158:161], v[224:227], v[30:33]
	v_mfma_f32_16x16x32_bf16 v[22:25], v[150:153], v[232:235], v[22:25]
	v_mfma_f32_16x16x32_bf16 v[14:17], v[158:161], v[232:235], v[14:17]
	v_mfma_f32_16x16x32_bf16 v[50:53], v[170:173], v[204:207], v[50:53]
	v_mfma_f32_16x16x32_bf16 v[42:45], v[196:199], v[204:207], v[42:45]
	v_mfma_f32_16x16x32_bf16 v[34:37], v[170:173], v[212:215], v[34:37]
	v_mfma_f32_16x16x32_bf16 v[26:29], v[196:199], v[212:215], v[26:29]
	v_mfma_f32_16x16x32_bf16 v[18:21], v[170:173], v[220:223], v[18:21]
	v_mfma_f32_16x16x32_bf16 v[10:13], v[196:199], v[220:223], v[10:13]
	v_mfma_f32_16x16x32_bf16 v[6:9], v[170:173], v[228:231], v[6:9]
	v_mfma_f32_16x16x32_bf16 v[2:5], v[196:199], v[228:231], v[2:5]
	v_mfma_f32_16x16x32_bf16 v[50:53], v[174:177], v[208:211], v[50:53]
	v_mfma_f32_16x16x32_bf16 v[42:45], v[200:203], v[208:211], v[42:45]
	v_mfma_f32_16x16x32_bf16 v[34:37], v[174:177], v[216:219], v[34:37]
	v_mfma_f32_16x16x32_bf16 v[26:29], v[200:203], v[216:219], v[26:29]
	v_mfma_f32_16x16x32_bf16 v[18:21], v[174:177], v[224:227], v[18:21]
	v_mfma_f32_16x16x32_bf16 v[10:13], v[200:203], v[224:227], v[10:13]
	v_mfma_f32_16x16x32_bf16 v[6:9], v[174:177], v[232:235], v[6:9]
	v_mfma_f32_16x16x32_bf16 v[2:5], v[200:203], v[232:235], v[2:5]
	s_setprio 0
	s_barrier
	s_add_u32 s90, s90, 0x100
	s_addc_u32 s91, s91, 0
	s_add_u32 s53, s53, 0x100
	s_addc_u32 vcc_lo, vcc_lo, 0
	s_cmp_ge_u32 vcc_hi, s37
	s_mov_b32 s92, vcc_hi
	s_cbranch_scc0 .LBB0_466
	s_and_b64 vcc, exec, s[86:87]
	s_cbranch_vccz .LBB0_469
	s_barrier

; DI const char* a_of(const Gemm& g, const Unit& u) { return (const char*)(g.A + (size_t)u.pz * g.zA + (size_t)u.pm * BM * g.lda); }
; DI const char* b_of(const Gemm& g, const Unit& u) { return (const char*)(g.Bt + (size_t)u.pz * g.zB + (size_t)u.pn * BM * g.ldb); }
; #define PG8_STAGE(bufoff, gbase, voff) do { _Pragma("unroll") for (int _i = 0; _i < 2; ++_i) \
;         __builtin_amdgcn_global_load_lds((const unsigned*)((const char*)(gbase) + (voff)[_i]), (LAS unsigned*)(lds + (bufoff) + ldsw + _i * 8192), 16, 0, 0); } while (0)
; #define PG8_LDA(dst, b, h) do { _Pragma("unroll") for (int m = 0; m < 4; ++m) _Pragma("unroll") for (int k = 0; k < 2; ++k) dst[m][k] = *(const LAS bf16x8*)(lds + PG8_SA(b, h) + aoff + m * 2048 + k * 1024); } while (0)
; #define PG8_LDB(dst, b, h) do { _Pragma("unroll") for (int n = 0; n < 2; ++n) _Pragma("unroll") for (int k = 0; k < 2; ++k) dst[n][k] = *(const LAS bf16x8*)(lds + PG8_SB(b, h) + boff + n * 2048 + k * 1024); } while (0)
; #define PG8_WAIT_V(n) asm volatile("s_waitcnt vmcnt(" #n ")" ::: "memory")
; #define PG8_WAIT_L(n) asm volatile("s_waitcnt lgkmcnt(" #n ")" ::: "memory")
; #define PG8_BAR __builtin_amdgcn_s_barrier()
; template <class Epi>
; DI void gemm_phase(LAS unsigned char* lds, int tid, const Gemm g, const Order& S, const Epi& E) {
;     ...
;         const bool has_next = S.next(ui + 1, nxt);
;         const char* nA = has_next ? a_of(g, nxt) : cA; const char* nB = has_next ? b_of(g, nxt) : cB;
; #pragma unroll 1
;         for (int t = 0; t < nt; t += 2) {
;             const bool last = (t == nt - 2);
;             const char* a1 = cA + (size_t)(t + 1) * kstep;
;             const char* a2 = last ? nA : cA + (size_t)(t + 2) * kstep; const char* b2 = last ? nB : cB + (size_t)(t + 2) * kstep;
;             const char* a3 = a2 + kstep; const char* b3 = b2 + kstep;
;             PG8_LDB(B0, 0, 0); PG8_LDB(B1, 0, 1); PG8_SCHED; PG8_LDA(At, 0, 0); PG8_STAGE(PG8_SA(1, 1), a1 + hstepA, voffA);
;             PG8_WAIT_V(8); PG8_WAIT_L(0); PG8_BAR; PG8_MMA(0, 0, At, B0); PG8_MMA(0, 1, At, B1); PG8_BAR; PG8_SCHED;
;             PG8_LDA(At, 0, 1); PG8_STAGE(PG8_SB(0, 0), b2, voffB); PG8_STAGE(PG8_SB(0, 1), b2 + hstepB, voffB); PG8_STAGE(PG8_SA(0, 0), a2, voffA);
;             PG8_WAIT_V(8); PG8_WAIT_L(0); PG8_BAR; PG8_MMA(1, 0, At, B0); PG8_MMA(1, 1, At, B1); PG8_BAR; PG8_SCHED;
.LBB0_493:
	s_add_i32 s40, s33, 2
	s_add_u32 s41, s84, 0x80
	s_addc_u32 s45, s85, 0
	s_add_i32 s47, 0, 0x10000
	s_cmp_eq_u32 s36, s33
	s_cselect_b32 s87, s7, s45
	s_cselect_b32 s86, s6, s41
	s_cselect_b32 s53, s83, s31
	s_cselect_b32 s52, s82, s30
	s_add_i32 s33, 0, 0x14000
	v_add_u32_e32 v152, s47, v168
	v_add_u32_e32 v160, s33, v168
	ds_read_b128 v[140:143], v152
	ds_read_b128 v[144:147], v152 offset:1024
	ds_read_b128 v[148:151], v152 offset:2048
	ds_read_b128 v[152:155], v152 offset:3072
	ds_read_b128 v[156:159], v160
	ds_read_b128 v[172:175], v160 offset:1024
	ds_read_b128 v[176:179], v160 offset:2048
	ds_read_b128 v[196:199], v160 offset:3072
	v_lshl_add_u64 v[160:161], s[84:85], 0, v[136:137]
	s_add_i32 m0, s46, 0xc000
	ds_read_b128 v[200:203], v171
	ds_read_b128 v[204:207], v171 offset:1024
	ds_read_b128 v[208:211], v171 offset:2048
	ds_read_b128 v[212:215], v171 offset:3072
	ds_read_b128 v[216:219], v171 offset:4096
	ds_read_b128 v[220:223], v171 offset:5120
	ds_read_b128 v[224:227], v171 offset:6144
	ds_read_b128 v[228:231], v171 offset:7168
	global_load_lds_dwordx4 v[160:161], off
	v_lshl_add_u64 v[160:161], s[84:85], 0, v[138:139]
	s_add_i32 m0, s46, 0xe000
	s_nop 0
	global_load_lds_dwordx4 v[160:161], off
	s_waitcnt vmcnt(8)
	s_waitcnt lgkmcnt(0)
	s_barrier
	s_setprio 1
	s_waitcnt lgkmcnt(0)
	v_mfma_f32_16x16x32_bf16 v[126:129], v[140:143], v[200:203], v[126:129]
	v_mfma_f32_16x16x32_bf16 v[122:125], v[148:151], v[200:203], v[122:125]
	v_mfma_f32_16x16x32_bf16 v[118:121], v[140:143], v[208:211], v[118:121]
	v_mfma_f32_16x16x32_bf16 v[114:117], v[148:151], v[208:211], v[114:117]
	v_mfma_f32_16x16x32_bf16 v[94:97], v[140:143], v[216:219], v[94:97]
	v_mfma_f32_16x16x32_bf16 v[90:93], v[148:151], v[216:219], v[90:93]
	v_mfma_f32_16x16x32_bf16 v[86:89], v[140:143], v[224:227], v[86:89]
	v_mfma_f32_16x16x32_bf16 v[82:85], v[148:151], v[224:227], v[82:85]
	v_mfma_f32_16x16x32_bf16 v[126:129], v[144:147], v[204:207], v[126:129]
	v_mfma_f32_16x16x32_bf16 v[122:125], v[152:155], v[204:207], v[122:125]
	v_mfma_f32_16x16x32_bf16 v[118:121], v[144:147], v[212:215], v[118:121]
	v_mfma_f32_16x16x32_bf16 v[114:117], v[152:155], v[212:215], v[114:117]
	v_mfma_f32_16x16x32_bf16 v[94:97], v[144:147], v[220:223], v[94:97]
	v_mfma_f32_16x16x32_bf16 v[90:93], v[152:155], v[220:223], v[90:93]
	v_mfma_f32_16x16x32_bf16 v[86:89], v[144:147], v[228:231], v[86:89]
	v_mfma_f32_16x16x32_bf16 v[82:85], v[152:155], v[228:231], v[82:85]
	v_mfma_f32_16x16x32_bf16 v[110:113], v[156:159], v[200:203], v[110:113]
	v_mfma_f32_16x16x32_bf16 v[106:109], v[176:179], v[200:203], v[106:109]
	v_mfma_f32_16x16x32_bf16 v[102:105], v[156:159], v[208:211], v[102:105]
	v_mfma_f32_16x16x32_bf16 v[98:101], v[176:179], v[208:211], v[98:101]
	v_mfma_f32_16x16x32_bf16 v[78:81], v[156:159], v[216:219], v[78:81]
	v_mfma_f32_16x16x32_bf16 v[74:77], v[176:179], v[216:219], v[74:77]
	v_mfma_f32_16x16x32_bf16 v[70:73], v[156:159], v[224:227], v[70:73]
	v_mfma_f32_16x16x32_bf16 v[66:69], v[176:179], v[224:227], v[66:69]
	v_mfma_f32_16x16x32_bf16 v[110:113], v[172:175], v[204:207], v[110:113]
	v_mfma_f32_16x16x32_bf16 v[106:109], v[196:199], v[204:207], v[106:109]
	v_mfma_f32_16x16x32_bf16 v[102:105], v[172:175], v[212:215], v[102:105]
	v_mfma_f32_16x16x32_bf16 v[98:101], v[196:199], v[212:215], v[98:101]
	v_mfma_f32_16x16x32_bf16 v[78:81], v[172:175], v[220:223], v[78:81]
	v_mfma_f32_16x16x32_bf16 v[74:77], v[196:199], v[220:223], v[74:77]
	v_mfma_f32_16x16x32_bf16 v[70:73], v[172:175], v[228:231], v[70:73]
	v_mfma_f32_16x16x32_bf16 v[66:69], v[196:199], v[228:231], v[66:69]
	s_setprio 0
	s_barrier
	s_add_i32 s41, s47, s10
	v_lshl_add_u64 v[160:161], s[52:53], 0, v[0:1]
	s_mov_b32 m0, s41
	ds_read_b128 v[200:203], v171 offset:16384
	ds_read_b128 v[204:207], v171 offset:17408
	ds_read_b128 v[208:211], v171 offset:18432
	ds_read_b128 v[212:215], v171 offset:19456
	ds_read_b128 v[216:219], v171 offset:20480
	ds_read_b128 v[220:223], v171 offset:21504
	ds_read_b128 v[224:227], v171 offset:22528
	ds_read_b128 v[228:231], v171 offset:23552
	global_load_lds_dwordx4 v[160:161], off
	s_add_i32 m0, s41, 0x2000
	v_lshl_add_u64 v[166:167], s[52:53], 0, v[130:131]
	s_add_u32 s52, s52, s20
	s_addc_u32 s53, s53, 0
	s_add_i32 s33, s33, s10
	global_load_lds_dwordx4 v[166:167], off
	v_lshl_add_u64 v[188:189], s[52:53], 0, v[0:1]
	s_mov_b32 m0, s33
	v_lshl_add_u64 v[190:191], s[52:53], 0, v[130:131]
	global_load_lds_dwordx4 v[188:189], off
	s_add_i32 m0, s33, 0x2000
	v_lshl_add_u64 v[232:233], s[86:87], 0, v[134:135]
	global_load_lds_dwordx4 v[190:191], off
	s_mov_b32 m0, s46
	v_lshl_add_u64 v[234:235], s[86:87], 0, v[132:133]
	global_load_lds_dwordx4 v[232:233], off
	s_mov_b32 m0, s49
	s_nop 0
	global_load_lds_dwordx4 v[234:235], off
	s_waitcnt vmcnt(8)
	s_waitcnt lgkmcnt(0)
	s_barrier
; #define PG8_STAGE(bufoff, gbase, voff) do { _Pragma("unroll") for (int _i = 0; _i < 2; ++_i) \
;         __builtin_amdgcn_global_load_lds((const unsigned*)((const char*)(gbase) + (voff)[_i]), (LAS unsigned*)(lds + (bufoff) + ldsw + _i * 8192), 16, 0, 0); } while (0)
; #define PG8_LDA(dst, b, h) do { _Pragma("unroll") for (int m = 0; m < 4; ++m) _Pragma("unroll") for (int k = 0; k < 2; ++k) dst[m][k] = *(const LAS bf16x8*)(lds + PG8_SA(b, h) + aoff + m * 2048 + k * 1024); } while (0)
; #define PG8_LDB(dst, b, h) do { _Pragma("unroll") for (int n = 0; n < 2; ++n) _Pragma("unroll") for (int k = 0; k < 2; ++k) dst[n][k] = *(const LAS bf16x8*)(lds + PG8_SB(b, h) + boff + n * 2048 + k * 1024); } while (0)
; #define PG8_MMA(ai, bj, At, Bt) do { __builtin_amdgcn_s_setprio(1); _Pragma("unroll") for (int m = 0; m < 4; ++m) _Pragma("unroll") for (int n = 0; n < 2; ++n) _Pragma("unroll") for (int k = 0; k < 2; ++k) \
;         acc[ai][bj][m][n] = __builtin_amdgcn_mfma_f32_16x16x32_bf16(Bt[n][k], At[m][k], acc[ai][bj][m][n], 0, 0, 0); __builtin_amdgcn_s_setprio(0); } while (0)
; #define PG8_WAIT_V(n) asm volatile("s_waitcnt vmcnt(" #n ")" ::: "memory")
; #define PG8_WAIT_L(n) asm volatile("s_waitcnt lgkmcnt(" #n ")" ::: "memory")
; #define PG8_BAR __builtin_amdgcn_s_barrier()
; #define PG8_SCHED __builtin_amdgcn_sched_barrier(0)
; template <class Epi>
; DI void gemm_phase(LAS unsigned char* lds, int tid, const Gemm g, const Order& S, const Epi& E) {
;     ...
;             PG8_WAIT_V(8); PG8_WAIT_L(0); PG8_BAR; PG8_MMA(1, 0, At, B0); PG8_MMA(1, 1, At, B1); PG8_BAR; PG8_SCHED;
;             PG8_LDB(B0, 1, 0); PG8_LDB(B1, 1, 1); PG8_SCHED; PG8_LDA(At, 1, 0); PG8_STAGE(PG8_SA(0, 1), a2 + hstepA, voffA);
;             PG8_WAIT_V(8); PG8_WAIT_L(0); PG8_BAR; PG8_MMA(0, 0, At, B0); PG8_MMA(0, 1, At, B1); PG8_BAR; PG8_SCHED;
	s_setprio 1
	s_waitcnt lgkmcnt(0)
	v_mfma_f32_16x16x32_bf16 v[62:65], v[140:143], v[200:203], v[62:65]
	v_mfma_f32_16x16x32_bf16 v[58:61], v[148:151], v[200:203], v[58:61]
	v_mfma_f32_16x16x32_bf16 v[54:57], v[140:143], v[208:211], v[54:57]
	v_mfma_f32_16x16x32_bf16 v[50:53], v[148:151], v[208:211], v[50:53]
	v_mfma_f32_16x16x32_bf16 v[30:33], v[140:143], v[216:219], v[30:33]
	v_mfma_f32_16x16x32_bf16 v[26:29], v[148:151], v[216:219], v[26:29]
	v_mfma_f32_16x16x32_bf16 v[22:25], v[140:143], v[224:227], v[22:25]
	v_mfma_f32_16x16x32_bf16 v[18:21], v[148:151], v[224:227], v[18:21]
	v_mfma_f32_16x16x32_bf16 v[62:65], v[144:147], v[204:207], v[62:65]
	v_mfma_f32_16x16x32_bf16 v[58:61], v[152:155], v[204:207], v[58:61]
	v_mfma_f32_16x16x32_bf16 v[54:57], v[144:147], v[212:215], v[54:57]
	v_mfma_f32_16x16x32_bf16 v[50:53], v[152:155], v[212:215], v[50:53]
	v_mfma_f32_16x16x32_bf16 v[30:33], v[144:147], v[220:223], v[30:33]
	v_mfma_f32_16x16x32_bf16 v[26:29], v[152:155], v[220:223], v[26:29]
	v_mfma_f32_16x16x32_bf16 v[22:25], v[144:147], v[228:231], v[22:25]
	v_mfma_f32_16x16x32_bf16 v[18:21], v[152:155], v[228:231], v[18:21]
	v_mfma_f32_16x16x32_bf16 v[46:49], v[156:159], v[200:203], v[46:49]
	v_mfma_f32_16x16x32_bf16 v[42:45], v[176:179], v[200:203], v[42:45]
	v_mfma_f32_16x16x32_bf16 v[38:41], v[156:159], v[208:211], v[38:41]
	v_mfma_f32_16x16x32_bf16 v[34:37], v[176:179], v[208:211], v[34:37]
	v_mfma_f32_16x16x32_bf16 v[14:17], v[156:159], v[216:219], v[14:17]
	v_mfma_f32_16x16x32_bf16 v[10:13], v[176:179], v[216:219], v[10:13]
	v_mfma_f32_16x16x32_bf16 v[6:9], v[156:159], v[224:227], v[6:9]
	v_mfma_f32_16x16x32_bf16 v[2:5], v[176:179], v[224:227], v[2:5]
	v_mfma_f32_16x16x32_bf16 v[46:49], v[172:175], v[204:207], v[46:49]
	v_mfma_f32_16x16x32_bf16 v[42:45], v[196:199], v[204:207], v[42:45]
	v_mfma_f32_16x16x32_bf16 v[38:41], v[172:175], v[212:215], v[38:41]
	v_mfma_f32_16x16x32_bf16 v[34:37], v[196:199], v[212:215], v[34:37]
	v_mfma_f32_16x16x32_bf16 v[14:17], v[172:175], v[220:223], v[14:17]
	v_mfma_f32_16x16x32_bf16 v[10:13], v[196:199], v[220:223], v[10:13]
	v_mfma_f32_16x16x32_bf16 v[6:9], v[172:175], v[228:231], v[6:9]
	v_mfma_f32_16x16x32_bf16 v[2:5], v[196:199], v[228:231], v[2:5]
	s_setprio 0
	s_barrier
	s_add_i32 s33, 0, 0x18000
	s_add_i32 s41, 0, 0x1c000
	v_add_u32_e32 v152, s33, v168
	v_add_u32_e32 v184, s41, v168
	ds_read_b128 v[140:143], v152
	ds_read_b128 v[144:147], v152 offset:1024
	ds_read_b128 v[148:151], v152 offset:2048
	ds_read_b128 v[152:155], v152 offset:3072
	ds_read_b128 v[156:159], v184
	ds_read_b128 v[172:175], v184 offset:1024
	ds_read_b128 v[176:179], v184 offset:2048
	ds_read_b128 v[196:199], v184 offset:3072
	s_add_u32 s52, s86, s20
	s_addc_u32 s53, s87, 0
	s_mov_b32 m0, s92
	v_lshl_add_u64 v[236:237], s[52:53], 0, v[134:135]
	ds_read_b128 v[200:203], v171 offset:32768
	ds_read_b128 v[204:207], v171 offset:33792
	ds_read_b128 v[208:211], v171 offset:34816
	ds_read_b128 v[212:215], v171 offset:35840
	ds_read_b128 v[216:219], v171 offset:36864
	ds_read_b128 v[220:223], v171 offset:37888
	ds_read_b128 v[224:227], v171 offset:38912
	ds_read_b128 v[228:231], v171 offset:39936
	global_load_lds_dwordx4 v[236:237], off
	v_lshl_add_u64 v[236:237], s[52:53], 0, v[132:133]
	s_mov_b32 m0, s93
	s_nop 0
	global_load_lds_dwordx4 v[236:237], off
	s_waitcnt vmcnt(8)
	s_waitcnt lgkmcnt(0)
	s_barrier
	s_setprio 1
	s_waitcnt lgkmcnt(0)
	v_mfma_f32_16x16x32_bf16 v[126:129], v[140:143], v[200:203], v[126:129]
	v_mfma_f32_16x16x32_bf16 v[122:125], v[148:151], v[200:203], v[122:125]
	v_mfma_f32_16x16x32_bf16 v[118:121], v[140:143], v[208:211], v[118:121]
	v_mfma_f32_16x16x32_bf16 v[114:117], v[148:151], v[208:211], v[114:117]
	v_mfma_f32_16x16x32_bf16 v[94:97], v[140:143], v[216:219], v[94:97]
	v_mfma_f32_16x16x32_bf16 v[90:93], v[148:151], v[216:219], v[90:93]
	v_mfma_f32_16x16x32_bf16 v[86:89], v[140:143], v[224:227], v[86:89]
	v_mfma_f32_16x16x32_bf16 v[82:85], v[148:151], v[224:227], v[82:85]
	v_mfma_f32_16x16x32_bf16 v[126:129], v[144:147], v[204:207], v[126:129]
	v_mfma_f32_16x16x32_bf16 v[122:125], v[152:155], v[204:207], v[122:125]
	v_mfma_f32_16x16x32_bf16 v[118:121], v[144:147], v[212:215], v[118:121]
	v_mfma_f32_16x16x32_bf16 v[114:117], v[152:155], v[212:215], v[114:117]
	v_mfma_f32_16x16x32_bf16 v[94:97], v[144:147], v[220:223], v[94:97]
	v_mfma_f32_16x16x32_bf16 v[90:93], v[152:155], v[220:223], v[90:93]
	v_mfma_f32_16x16x32_bf16 v[86:89], v[144:147], v[228:231], v[86:89]
	v_mfma_f32_16x16x32_bf16 v[82:85], v[152:155], v[228:231], v[82:85]
	v_mfma_f32_16x16x32_bf16 v[110:113], v[156:159], v[200:203], v[110:113]
	v_mfma_f32_16x16x32_bf16 v[106:109], v[176:179], v[200:203], v[106:109]
	v_mfma_f32_16x16x32_bf16 v[102:105], v[156:159], v[208:211], v[102:105]
	v_mfma_f32_16x16x32_bf16 v[98:101], v[176:179], v[208:211], v[98:101]
	v_mfma_f32_16x16x32_bf16 v[78:81], v[156:159], v[216:219], v[78:81]
	v_mfma_f32_16x16x32_bf16 v[74:77], v[176:179], v[216:219], v[74:77]
	v_mfma_f32_16x16x32_bf16 v[70:73], v[156:159], v[224:227], v[70:73]
	v_mfma_f32_16x16x32_bf16 v[66:69], v[176:179], v[224:227], v[66:69]
	v_mfma_f32_16x16x32_bf16 v[110:113], v[172:175], v[204:207], v[110:113]
	v_mfma_f32_16x16x32_bf16 v[106:109], v[196:199], v[204:207], v[106:109]
	v_mfma_f32_16x16x32_bf16 v[102:105], v[172:175], v[212:215], v[102:105]
	v_mfma_f32_16x16x32_bf16 v[98:101], v[196:199], v[212:215], v[98:101]
	v_mfma_f32_16x16x32_bf16 v[78:81], v[172:175], v[220:223], v[78:81]
	v_mfma_f32_16x16x32_bf16 v[74:77], v[196:199], v[220:223], v[74:77]
	v_mfma_f32_16x16x32_bf16 v[70:73], v[172:175], v[228:231], v[70:73]
	v_mfma_f32_16x16x32_bf16 v[66:69], v[196:199], v[228:231], v[66:69]
	s_setprio 0
	s_barrier
; #define PG8_STAGE(bufoff, gbase, voff) do { _Pragma("unroll") for (int _i = 0; _i < 2; ++_i) \
;         __builtin_amdgcn_global_load_lds((const unsigned*)((const char*)(gbase) + (voff)[_i]), (LAS unsigned*)(lds + (bufoff) + ldsw + _i * 8192), 16, 0, 0); } while (0)
; #define PG8_LDA(dst, b, h) do { _Pragma("unroll") for (int m = 0; m < 4; ++m) _Pragma("unroll") for (int k = 0; k < 2; ++k) dst[m][k] = *(const LAS bf16x8*)(lds + PG8_SA(b, h) + aoff + m * 2048 + k * 1024); } while (0)
; #define PG8_MMA(ai, bj, At, Bt) do { __builtin_amdgcn_s_setprio(1); _Pragma("unroll") for (int m = 0; m < 4; ++m) _Pragma("unroll") for (int n = 0; n < 2; ++n) _Pragma("unroll") for (int k = 0; k < 2; ++k) \
;         acc[ai][bj][m][n] = __builtin_amdgcn_mfma_f32_16x16x32_bf16(Bt[n][k], At[m][k], acc[ai][bj][m][n], 0, 0, 0); __builtin_amdgcn_s_setprio(0); } while (0)
; #define PG8_WAIT_V(n) asm volatile("s_waitcnt vmcnt(" #n ")" ::: "memory")
; #define PG8_WAIT_L(n) asm volatile("s_waitcnt lgkmcnt(" #n ")" ::: "memory")
; #define PG8_BAR __builtin_amdgcn_s_barrier()
; #define PG8_SCHED __builtin_amdgcn_sched_barrier(0)
; template <class Epi>
; DI void gemm_phase(LAS unsigned char* lds, int tid, const Gemm g, const Order& S, const Epi& E) {
;     ...
;             PG8_LDA(At, 1, 1); PG8_STAGE(PG8_SB(1, 0), b3, voffB); PG8_STAGE(PG8_SB(1, 1), b3 + hstepB, voffB); PG8_STAGE(PG8_SA(1, 0), a3, voffA);
;             PG8_WAIT_V(8); PG8_WAIT_L(0); PG8_BAR; PG8_MMA(1, 0, At, B0); PG8_MMA(1, 1, At, B1); PG8_BAR; PG8_SCHED;
;         }
;         if (wr == 0) PG8_BAR;
	s_add_i32 s33, s33, s10
	v_lshl_add_u64 v[160:161], v[160:161], 0, s[24:25]
	s_mov_b32 m0, s33
	ds_read_b128 v[200:203], v171 offset:49152
	ds_read_b128 v[204:207], v171 offset:50176
	ds_read_b128 v[208:211], v171 offset:51200
	ds_read_b128 v[212:215], v171 offset:52224
	ds_read_b128 v[216:219], v171 offset:53248
	ds_read_b128 v[220:223], v171 offset:54272
	ds_read_b128 v[224:227], v171 offset:55296
	ds_read_b128 v[228:231], v171 offset:56320
	global_load_lds_dwordx4 v[160:161], off
	v_lshl_add_u64 v[160:161], v[166:167], 0, s[24:25]
	s_add_i32 m0, s33, 0x2000
	s_add_i32 s33, s41, s10
	global_load_lds_dwordx4 v[160:161], off
	v_lshl_add_u64 v[160:161], v[188:189], 0, s[24:25]
	s_mov_b32 m0, s33
	s_nop 0
	global_load_lds_dwordx4 v[160:161], off
	v_lshl_add_u64 v[160:161], v[190:191], 0, s[24:25]
	s_add_i32 m0, s33, 0x2000
	s_nop 0
	global_load_lds_dwordx4 v[160:161], off
	v_lshl_add_u64 v[160:161], v[232:233], 0, s[24:25]
	s_mov_b32 m0, s37
	s_nop 0
	global_load_lds_dwordx4 v[160:161], off
	v_lshl_add_u64 v[160:161], v[234:235], 0, s[24:25]
	s_mov_b32 m0, s39
	s_nop 0
	global_load_lds_dwordx4 v[160:161], off
	s_waitcnt vmcnt(8)
	s_waitcnt lgkmcnt(0)
	s_barrier
	s_setprio 1
	s_waitcnt lgkmcnt(0)
	v_mfma_f32_16x16x32_bf16 v[62:65], v[140:143], v[200:203], v[62:65]
	v_mfma_f32_16x16x32_bf16 v[58:61], v[148:151], v[200:203], v[58:61]
	v_mfma_f32_16x16x32_bf16 v[54:57], v[140:143], v[208:211], v[54:57]
	v_mfma_f32_16x16x32_bf16 v[50:53], v[148:151], v[208:211], v[50:53]
	v_mfma_f32_16x16x32_bf16 v[30:33], v[140:143], v[216:219], v[30:33]
	v_mfma_f32_16x16x32_bf16 v[26:29], v[148:151], v[216:219], v[26:29]
	v_mfma_f32_16x16x32_bf16 v[22:25], v[140:143], v[224:227], v[22:25]
	v_mfma_f32_16x16x32_bf16 v[18:21], v[148:151], v[224:227], v[18:21]
	v_mfma_f32_16x16x32_bf16 v[62:65], v[144:147], v[204:207], v[62:65]
	v_mfma_f32_16x16x32_bf16 v[58:61], v[152:155], v[204:207], v[58:61]
	v_mfma_f32_16x16x32_bf16 v[54:57], v[144:147], v[212:215], v[54:57]
	v_mfma_f32_16x16x32_bf16 v[50:53], v[152:155], v[212:215], v[50:53]
	v_mfma_f32_16x16x32_bf16 v[30:33], v[144:147], v[220:223], v[30:33]
	v_mfma_f32_16x16x32_bf16 v[26:29], v[152:155], v[220:223], v[26:29]
	v_mfma_f32_16x16x32_bf16 v[22:25], v[144:147], v[228:231], v[22:25]
	v_mfma_f32_16x16x32_bf16 v[18:21], v[152:155], v[228:231], v[18:21]
	v_mfma_f32_16x16x32_bf16 v[46:49], v[156:159], v[200:203], v[46:49]
	v_mfma_f32_16x16x32_bf16 v[42:45], v[176:179], v[200:203], v[42:45]
	v_mfma_f32_16x16x32_bf16 v[38:41], v[156:159], v[208:211], v[38:41]
	v_mfma_f32_16x16x32_bf16 v[34:37], v[176:179], v[208:211], v[34:37]
	v_mfma_f32_16x16x32_bf16 v[14:17], v[156:159], v[216:219], v[14:17]
	v_mfma_f32_16x16x32_bf16 v[10:13], v[176:179], v[216:219], v[10:13]
	v_mfma_f32_16x16x32_bf16 v[6:9], v[156:159], v[224:227], v[6:9]
	v_mfma_f32_16x16x32_bf16 v[2:5], v[176:179], v[224:227], v[2:5]
	v_mfma_f32_16x16x32_bf16 v[46:49], v[172:175], v[204:207], v[46:49]
	v_mfma_f32_16x16x32_bf16 v[42:45], v[196:199], v[204:207], v[42:45]
	v_mfma_f32_16x16x32_bf16 v[38:41], v[172:175], v[212:215], v[38:41]
	v_mfma_f32_16x16x32_bf16 v[34:37], v[196:199], v[212:215], v[34:37]
	v_mfma_f32_16x16x32_bf16 v[14:17], v[172:175], v[220:223], v[14:17]
	v_mfma_f32_16x16x32_bf16 v[10:13], v[196:199], v[220:223], v[10:13]
	v_mfma_f32_16x16x32_bf16 v[6:9], v[172:175], v[228:231], v[6:9]
	v_mfma_f32_16x16x32_bf16 v[2:5], v[196:199], v[228:231], v[2:5]
	s_setprio 0
	s_barrier
	s_add_u32 s84, s84, 0x100
	s_addc_u32 s85, s85, 0
	s_add_u32 s30, s30, 0x100
	s_addc_u32 s31, s31, 0
	s_cmp_ge_u32 s40, s28
	s_mov_b32 s33, s40
	s_cbranch_scc0 .LBB0_493
	s_and_b64 vcc, exec, s[80:81]
	s_cbranch_vccz .LBB0_496
	s_barrier

; DI const char* a_of(const Gemm& g, const Unit& u) { return (const char*)(g.A + (size_t)u.pz * g.zA + (size_t)u.pm * BM * g.lda); }
; DI const char* b_of(const Gemm& g, const Unit& u) { return (const char*)(g.Bt + (size_t)u.pz * g.zB + (size_t)u.pn * BM * g.ldb); }
; #define PG8_STAGE(bufoff, gbase, voff) do { _Pragma("unroll") for (int _i = 0; _i < 2; ++_i) \
;         __builtin_amdgcn_global_load_lds((const unsigned*)((const char*)(gbase) + (voff)[_i]), (LAS unsigned*)(lds + (bufoff) + ldsw + _i * 8192), 16, 0, 0); } while (0)
; #define PG8_LDA(dst, b, h) do { _Pragma("unroll") for (int m = 0; m < 4; ++m) _Pragma("unroll") for (int k = 0; k < 2; ++k) dst[m][k] = *(const LAS bf16x8*)(lds + PG8_SA(b, h) + aoff + m * 2048 + k * 1024); } while (0)
; #define PG8_LDB(dst, b, h) do { _Pragma("unroll") for (int n = 0; n < 2; ++n) _Pragma("unroll") for (int k = 0; k < 2; ++k) dst[n][k] = *(const LAS bf16x8*)(lds + PG8_SB(b, h) + boff + n * 2048 + k * 1024); } while (0)
; #define PG8_WAIT_V(n) asm volatile("s_waitcnt vmcnt(" #n ")" ::: "memory")
; #define PG8_WAIT_L(n) asm volatile("s_waitcnt lgkmcnt(" #n ")" ::: "memory")
; #define PG8_BAR __builtin_amdgcn_s_barrier()
; template <class Epi>
; DI void gemm_phase(LAS unsigned char* lds, int tid, const Gemm g, const Order& S, const Epi& E) {
;     ...
;         const bool has_next = S.next(ui + 1, nxt);
;         const char* nA = has_next ? a_of(g, nxt) : cA; const char* nB = has_next ? b_of(g, nxt) : cB;
; #pragma unroll 1
;         for (int t = 0; t < nt; t += 2) {
;             const bool last = (t == nt - 2);
;             const char* a1 = cA + (size_t)(t + 1) * kstep;
;             const char* a2 = last ? nA : cA + (size_t)(t + 2) * kstep; const char* b2 = last ? nB : cB + (size_t)(t + 2) * kstep;
;             const char* a3 = a2 + kstep; const char* b3 = b2 + kstep;
;             PG8_LDB(B0, 0, 0); PG8_LDB(B1, 0, 1); PG8_SCHED; PG8_LDA(At, 0, 0); PG8_STAGE(PG8_SA(1, 1), a1 + hstepA, voffA);
;             PG8_WAIT_V(8); PG8_WAIT_L(0); PG8_BAR; PG8_MMA(0, 0, At, B0); PG8_MMA(0, 1, At, B1); PG8_BAR; PG8_SCHED;
;             PG8_LDA(At, 0, 1); PG8_STAGE(PG8_SB(0, 0), b2, voffB); PG8_STAGE(PG8_SB(0, 1), b2 + hstepB, voffB); PG8_STAGE(PG8_SA(0, 0), a2, voffA);
;             PG8_WAIT_V(8); PG8_WAIT_L(0); PG8_BAR; PG8_MMA(1, 0, At, B0); PG8_MMA(1, 1, At, B1); PG8_BAR; PG8_SCHED;
.LBB0_513:
	s_add_u32 s48, s74, 0xfffc0080
	s_addc_u32 s49, s75, -1
	s_add_i32 s51, 0, 0x10000
	s_cmp_eq_u32 s47, 12
	s_cselect_b32 s79, s39, s49
	s_cselect_b32 s78, s40, s48
	s_cselect_b32 s77, s41, s46
	s_cselect_b32 s76, s43, s45
	s_add_i32 s52, 0, 0x14000
	v_add_u32_e32 v156, s51, v145
	v_add_u32_e32 v160, s52, v145
	ds_read_b128 v[140:143], v156
	ds_read_b128 v[148:151], v156 offset:1024
	ds_read_b128 v[152:155], v156 offset:2048
	ds_read_b128 v[156:159], v156 offset:3072
	ds_read_b128 v[164:167], v160
	ds_read_b128 v[170:173], v160 offset:1024
	ds_read_b128 v[174:177], v160 offset:2048
	ds_read_b128 v[196:199], v160 offset:3072
	v_lshl_add_u64 v[160:161], s[74:75], 0, v[136:137]
	s_add_i32 m0, s22, 0xc000
	ds_read_b128 v[200:203], v147
	ds_read_b128 v[204:207], v147 offset:1024
	ds_read_b128 v[208:211], v147 offset:2048
	ds_read_b128 v[212:215], v147 offset:3072
	ds_read_b128 v[216:219], v147 offset:4096
	ds_read_b128 v[220:223], v147 offset:5120
	ds_read_b128 v[224:227], v147 offset:6144
	ds_read_b128 v[228:231], v147 offset:7168
	global_load_lds_dwordx4 v[160:161], off
	v_lshl_add_u64 v[160:161], s[74:75], 0, v[138:139]
	s_add_i32 m0, s22, 0xe000
	s_nop 0
	global_load_lds_dwordx4 v[160:161], off
	s_waitcnt vmcnt(8)
	s_waitcnt lgkmcnt(0)
	s_barrier
	s_setprio 1
	s_waitcnt lgkmcnt(0)
	v_mfma_f32_16x16x32_bf16 v[126:129], v[140:143], v[200:203], v[126:129]
	v_mfma_f32_16x16x32_bf16 v[122:125], v[152:155], v[200:203], v[122:125]
	v_mfma_f32_16x16x32_bf16 v[110:113], v[140:143], v[208:211], v[110:113]
	v_mfma_f32_16x16x32_bf16 v[106:109], v[152:155], v[208:211], v[106:109]
	v_mfma_f32_16x16x32_bf16 v[94:97], v[140:143], v[216:219], v[94:97]
	v_mfma_f32_16x16x32_bf16 v[90:93], v[152:155], v[216:219], v[90:93]
	v_mfma_f32_16x16x32_bf16 v[78:81], v[140:143], v[224:227], v[78:81]
	v_mfma_f32_16x16x32_bf16 v[74:77], v[152:155], v[224:227], v[74:77]
	v_mfma_f32_16x16x32_bf16 v[126:129], v[148:151], v[204:207], v[126:129]
	v_mfma_f32_16x16x32_bf16 v[122:125], v[156:159], v[204:207], v[122:125]
	v_mfma_f32_16x16x32_bf16 v[110:113], v[148:151], v[212:215], v[110:113]
	v_mfma_f32_16x16x32_bf16 v[106:109], v[156:159], v[212:215], v[106:109]
	v_mfma_f32_16x16x32_bf16 v[94:97], v[148:151], v[220:223], v[94:97]
	v_mfma_f32_16x16x32_bf16 v[90:93], v[156:159], v[220:223], v[90:93]
	v_mfma_f32_16x16x32_bf16 v[78:81], v[148:151], v[228:231], v[78:81]
	v_mfma_f32_16x16x32_bf16 v[74:77], v[156:159], v[228:231], v[74:77]
	v_mfma_f32_16x16x32_bf16 v[118:121], v[164:167], v[200:203], v[118:121]
	v_mfma_f32_16x16x32_bf16 v[114:117], v[174:177], v[200:203], v[114:117]
	v_mfma_f32_16x16x32_bf16 v[102:105], v[164:167], v[208:211], v[102:105]
	v_mfma_f32_16x16x32_bf16 v[98:101], v[174:177], v[208:211], v[98:101]
	v_mfma_f32_16x16x32_bf16 v[86:89], v[164:167], v[216:219], v[86:89]
	v_mfma_f32_16x16x32_bf16 v[82:85], v[174:177], v[216:219], v[82:85]
	v_mfma_f32_16x16x32_bf16 v[70:73], v[164:167], v[224:227], v[70:73]
	v_mfma_f32_16x16x32_bf16 v[66:69], v[174:177], v[224:227], v[66:69]
	v_mfma_f32_16x16x32_bf16 v[118:121], v[170:173], v[204:207], v[118:121]
	v_mfma_f32_16x16x32_bf16 v[114:117], v[196:199], v[204:207], v[114:117]
	v_mfma_f32_16x16x32_bf16 v[102:105], v[170:173], v[212:215], v[102:105]
	v_mfma_f32_16x16x32_bf16 v[98:101], v[196:199], v[212:215], v[98:101]
	v_mfma_f32_16x16x32_bf16 v[86:89], v[170:173], v[220:223], v[86:89]
	v_mfma_f32_16x16x32_bf16 v[82:85], v[196:199], v[220:223], v[82:85]
	v_mfma_f32_16x16x32_bf16 v[70:73], v[170:173], v[228:231], v[70:73]
	v_mfma_f32_16x16x32_bf16 v[66:69], v[196:199], v[228:231], v[66:69]
	s_setprio 0
	s_barrier
	s_add_i32 s48, s51, s17
	v_lshl_add_u64 v[160:161], s[76:77], 0, v[0:1]
	s_mov_b32 m0, s48
	ds_read_b128 v[200:203], v147 offset:16384
	ds_read_b128 v[204:207], v147 offset:17408
	ds_read_b128 v[208:211], v147 offset:18432
	ds_read_b128 v[212:215], v147 offset:19456
	ds_read_b128 v[216:219], v147 offset:20480
	ds_read_b128 v[220:223], v147 offset:21504
	ds_read_b128 v[224:227], v147 offset:22528
	ds_read_b128 v[228:231], v147 offset:23552
	global_load_lds_dwordx4 v[160:161], off
	s_add_i32 m0, s48, 0x2000
	s_add_u32 s48, s76, 0x40000
	v_lshl_add_u64 v[178:179], s[76:77], 0, v[134:135]
	s_addc_u32 s49, s77, 0
	s_add_i32 s51, s52, s17
	global_load_lds_dwordx4 v[178:179], off
	v_lshl_add_u64 v[188:189], s[48:49], 0, v[0:1]
	s_mov_b32 m0, s51
	v_lshl_add_u64 v[190:191], s[78:79], 0, v[132:133]
	global_load_lds_dwordx4 v[188:189], off
	v_lshl_add_u64 v[188:189], s[48:49], 0, v[134:135]
	s_add_i32 m0, s51, 0x2000
	s_nop 0
	global_load_lds_dwordx4 v[188:189], off
	v_lshl_add_u64 v[188:189], s[78:79], 0, v[130:131]
	s_mov_b32 m0, s22
	s_nop 0
	global_load_lds_dwordx4 v[188:189], off
	s_mov_b32 m0, s26
	s_nop 0
	global_load_lds_dwordx4 v[190:191], off
	s_waitcnt vmcnt(8)
	s_waitcnt lgkmcnt(0)
	s_barrier
; #define PG8_STAGE(bufoff, gbase, voff) do { _Pragma("unroll") for (int _i = 0; _i < 2; ++_i) \
;         __builtin_amdgcn_global_load_lds((const unsigned*)((const char*)(gbase) + (voff)[_i]), (LAS unsigned*)(lds + (bufoff) + ldsw + _i * 8192), 16, 0, 0); } while (0)
; #define PG8_LDA(dst, b, h) do { _Pragma("unroll") for (int m = 0; m < 4; ++m) _Pragma("unroll") for (int k = 0; k < 2; ++k) dst[m][k] = *(const LAS bf16x8*)(lds + PG8_SA(b, h) + aoff + m * 2048 + k * 1024); } while (0)
; #define PG8_LDB(dst, b, h) do { _Pragma("unroll") for (int n = 0; n < 2; ++n) _Pragma("unroll") for (int k = 0; k < 2; ++k) dst[n][k] = *(const LAS bf16x8*)(lds + PG8_SB(b, h) + boff + n * 2048 + k * 1024); } while (0)
; #define PG8_MMA(ai, bj, At, Bt) do { __builtin_amdgcn_s_setprio(1); _Pragma("unroll") for (int m = 0; m < 4; ++m) _Pragma("unroll") for (int n = 0; n < 2; ++n) _Pragma("unroll") for (int k = 0; k < 2; ++k) \
;         acc[ai][bj][m][n] = __builtin_amdgcn_mfma_f32_16x16x32_bf16(Bt[n][k], At[m][k], acc[ai][bj][m][n], 0, 0, 0); __builtin_amdgcn_s_setprio(0); } while (0)
; #define PG8_WAIT_V(n) asm volatile("s_waitcnt vmcnt(" #n ")" ::: "memory")
; #define PG8_WAIT_L(n) asm volatile("s_waitcnt lgkmcnt(" #n ")" ::: "memory")
; #define PG8_BAR __builtin_amdgcn_s_barrier()
; #define PG8_SCHED __builtin_amdgcn_sched_barrier(0)
; template <class Epi>
; DI void gemm_phase(LAS unsigned char* lds, int tid, const Gemm g, const Order& S, const Epi& E) {
;     ...
;             PG8_WAIT_V(8); PG8_WAIT_L(0); PG8_BAR; PG8_MMA(1, 0, At, B0); PG8_MMA(1, 1, At, B1); PG8_BAR; PG8_SCHED;
;             PG8_LDB(B0, 1, 0); PG8_LDB(B1, 1, 1); PG8_SCHED; PG8_LDA(At, 1, 0); PG8_STAGE(PG8_SA(0, 1), a2 + hstepA, voffA);
;             PG8_WAIT_V(8); PG8_WAIT_L(0); PG8_BAR; PG8_MMA(0, 0, At, B0); PG8_MMA(0, 1, At, B1); PG8_BAR; PG8_SCHED;
	s_setprio 1
	s_waitcnt lgkmcnt(0)
	v_mfma_f32_16x16x32_bf16 v[62:65], v[140:143], v[200:203], v[62:65]
	v_mfma_f32_16x16x32_bf16 v[58:61], v[152:155], v[200:203], v[58:61]
	v_mfma_f32_16x16x32_bf16 v[46:49], v[140:143], v[208:211], v[46:49]
	v_mfma_f32_16x16x32_bf16 v[42:45], v[152:155], v[208:211], v[42:45]
	v_mfma_f32_16x16x32_bf16 v[30:33], v[140:143], v[216:219], v[30:33]
	v_mfma_f32_16x16x32_bf16 v[26:29], v[152:155], v[216:219], v[26:29]
	v_mfma_f32_16x16x32_bf16 v[14:17], v[140:143], v[224:227], v[14:17]
	v_mfma_f32_16x16x32_bf16 v[10:13], v[152:155], v[224:227], v[10:13]
	v_mfma_f32_16x16x32_bf16 v[62:65], v[148:151], v[204:207], v[62:65]
	v_mfma_f32_16x16x32_bf16 v[58:61], v[156:159], v[204:207], v[58:61]
	v_mfma_f32_16x16x32_bf16 v[46:49], v[148:151], v[212:215], v[46:49]
	v_mfma_f32_16x16x32_bf16 v[42:45], v[156:159], v[212:215], v[42:45]
	v_mfma_f32_16x16x32_bf16 v[30:33], v[148:151], v[220:223], v[30:33]
	v_mfma_f32_16x16x32_bf16 v[26:29], v[156:159], v[220:223], v[26:29]
	v_mfma_f32_16x16x32_bf16 v[14:17], v[148:151], v[228:231], v[14:17]
	v_mfma_f32_16x16x32_bf16 v[10:13], v[156:159], v[228:231], v[10:13]
	v_mfma_f32_16x16x32_bf16 v[54:57], v[164:167], v[200:203], v[54:57]
	v_mfma_f32_16x16x32_bf16 v[50:53], v[174:177], v[200:203], v[50:53]
	v_mfma_f32_16x16x32_bf16 v[38:41], v[164:167], v[208:211], v[38:41]
	v_mfma_f32_16x16x32_bf16 v[34:37], v[174:177], v[208:211], v[34:37]
	v_mfma_f32_16x16x32_bf16 v[22:25], v[164:167], v[216:219], v[22:25]
	v_mfma_f32_16x16x32_bf16 v[18:21], v[174:177], v[216:219], v[18:21]
	v_mfma_f32_16x16x32_bf16 v[6:9], v[164:167], v[224:227], v[6:9]
	v_mfma_f32_16x16x32_bf16 v[2:5], v[174:177], v[224:227], v[2:5]
	v_mfma_f32_16x16x32_bf16 v[54:57], v[170:173], v[204:207], v[54:57]
	v_mfma_f32_16x16x32_bf16 v[50:53], v[196:199], v[204:207], v[50:53]
	v_mfma_f32_16x16x32_bf16 v[38:41], v[170:173], v[212:215], v[38:41]
	v_mfma_f32_16x16x32_bf16 v[34:37], v[196:199], v[212:215], v[34:37]
	v_mfma_f32_16x16x32_bf16 v[22:25], v[170:173], v[220:223], v[22:25]
	v_mfma_f32_16x16x32_bf16 v[18:21], v[196:199], v[220:223], v[18:21]
	v_mfma_f32_16x16x32_bf16 v[6:9], v[170:173], v[228:231], v[6:9]
	v_mfma_f32_16x16x32_bf16 v[2:5], v[196:199], v[228:231], v[2:5]
	s_setprio 0
	s_barrier
	s_add_i32 s51, 0, 0x18000
	s_add_i32 s52, 0, 0x1c000
	v_add_u32_e32 v156, s51, v145
	v_add_u32_e32 v168, s52, v145
	ds_read_b128 v[140:143], v156
	ds_read_b128 v[148:151], v156 offset:1024
	ds_read_b128 v[152:155], v156 offset:2048
	ds_read_b128 v[156:159], v156 offset:3072
	ds_read_b128 v[164:167], v168
	ds_read_b128 v[170:173], v168 offset:1024
	ds_read_b128 v[174:177], v168 offset:2048
	ds_read_b128 v[196:199], v168 offset:3072
	s_add_u32 s48, s78, 0x40000
	s_addc_u32 s49, s79, 0
	s_mov_b32 m0, s28
	v_lshl_add_u64 v[232:233], s[48:49], 0, v[130:131]
	ds_read_b128 v[200:203], v147 offset:32768
	ds_read_b128 v[204:207], v147 offset:33792
	ds_read_b128 v[208:211], v147 offset:34816
	ds_read_b128 v[212:215], v147 offset:35840
	ds_read_b128 v[216:219], v147 offset:36864
	ds_read_b128 v[220:223], v147 offset:37888
	ds_read_b128 v[224:227], v147 offset:38912
	ds_read_b128 v[228:231], v147 offset:39936
	global_load_lds_dwordx4 v[232:233], off
	v_lshl_add_u64 v[232:233], s[48:49], 0, v[132:133]
	s_mov_b32 m0, s30
	s_nop 0
	global_load_lds_dwordx4 v[232:233], off
	s_waitcnt vmcnt(8)
	s_waitcnt lgkmcnt(0)
	s_barrier
	s_setprio 1
	s_waitcnt lgkmcnt(0)
	v_mfma_f32_16x16x32_bf16 v[126:129], v[140:143], v[200:203], v[126:129]
	v_mfma_f32_16x16x32_bf16 v[122:125], v[152:155], v[200:203], v[122:125]
	v_mfma_f32_16x16x32_bf16 v[110:113], v[140:143], v[208:211], v[110:113]
	v_mfma_f32_16x16x32_bf16 v[106:109], v[152:155], v[208:211], v[106:109]
	v_mfma_f32_16x16x32_bf16 v[94:97], v[140:143], v[216:219], v[94:97]
	v_mfma_f32_16x16x32_bf16 v[90:93], v[152:155], v[216:219], v[90:93]
	v_mfma_f32_16x16x32_bf16 v[78:81], v[140:143], v[224:227], v[78:81]
	v_mfma_f32_16x16x32_bf16 v[74:77], v[152:155], v[224:227], v[74:77]
	v_mfma_f32_16x16x32_bf16 v[126:129], v[148:151], v[204:207], v[126:129]
	v_mfma_f32_16x16x32_bf16 v[122:125], v[156:159], v[204:207], v[122:125]
	v_mfma_f32_16x16x32_bf16 v[110:113], v[148:151], v[212:215], v[110:113]
	v_mfma_f32_16x16x32_bf16 v[106:109], v[156:159], v[212:215], v[106:109]
	v_mfma_f32_16x16x32_bf16 v[94:97], v[148:151], v[220:223], v[94:97]
	v_mfma_f32_16x16x32_bf16 v[90:93], v[156:159], v[220:223], v[90:93]
	v_mfma_f32_16x16x32_bf16 v[78:81], v[148:151], v[228:231], v[78:81]
	v_mfma_f32_16x16x32_bf16 v[74:77], v[156:159], v[228:231], v[74:77]
	v_mfma_f32_16x16x32_bf16 v[118:121], v[164:167], v[200:203], v[118:121]
	v_mfma_f32_16x16x32_bf16 v[114:117], v[174:177], v[200:203], v[114:117]
	v_mfma_f32_16x16x32_bf16 v[102:105], v[164:167], v[208:211], v[102:105]
	v_mfma_f32_16x16x32_bf16 v[98:101], v[174:177], v[208:211], v[98:101]
	v_mfma_f32_16x16x32_bf16 v[86:89], v[164:167], v[216:219], v[86:89]
	v_mfma_f32_16x16x32_bf16 v[82:85], v[174:177], v[216:219], v[82:85]
	v_mfma_f32_16x16x32_bf16 v[70:73], v[164:167], v[224:227], v[70:73]
	v_mfma_f32_16x16x32_bf16 v[66:69], v[174:177], v[224:227], v[66:69]
	v_mfma_f32_16x16x32_bf16 v[118:121], v[170:173], v[204:207], v[118:121]
	v_mfma_f32_16x16x32_bf16 v[114:117], v[196:199], v[204:207], v[114:117]
	v_mfma_f32_16x16x32_bf16 v[102:105], v[170:173], v[212:215], v[102:105]
	v_mfma_f32_16x16x32_bf16 v[98:101], v[196:199], v[212:215], v[98:101]
	v_mfma_f32_16x16x32_bf16 v[86:89], v[170:173], v[220:223], v[86:89]
	v_mfma_f32_16x16x32_bf16 v[82:85], v[196:199], v[220:223], v[82:85]
	v_mfma_f32_16x16x32_bf16 v[70:73], v[170:173], v[228:231], v[70:73]
	v_mfma_f32_16x16x32_bf16 v[66:69], v[196:199], v[228:231], v[66:69]
	s_setprio 0
	s_barrier
; #define PG8_STAGE(bufoff, gbase, voff) do { _Pragma("unroll") for (int _i = 0; _i < 2; ++_i) \
;         __builtin_amdgcn_global_load_lds((const unsigned*)((const char*)(gbase) + (voff)[_i]), (LAS unsigned*)(lds + (bufoff) + ldsw + _i * 8192), 16, 0, 0); } while (0)
; #define PG8_LDA(dst, b, h) do { _Pragma("unroll") for (int m = 0; m < 4; ++m) _Pragma("unroll") for (int k = 0; k < 2; ++k) dst[m][k] = *(const LAS bf16x8*)(lds + PG8_SA(b, h) + aoff + m * 2048 + k * 1024); } while (0)
; #define PG8_MMA(ai, bj, At, Bt) do { __builtin_amdgcn_s_setprio(1); _Pragma("unroll") for (int m = 0; m < 4; ++m) _Pragma("unroll") for (int n = 0; n < 2; ++n) _Pragma("unroll") for (int k = 0; k < 2; ++k) \
;         acc[ai][bj][m][n] = __builtin_amdgcn_mfma_f32_16x16x32_bf16(Bt[n][k], At[m][k], acc[ai][bj][m][n], 0, 0, 0); __builtin_amdgcn_s_setprio(0); } while (0)
; #define PG8_WAIT_V(n) asm volatile("s_waitcnt vmcnt(" #n ")" ::: "memory")
; #define PG8_WAIT_L(n) asm volatile("s_waitcnt lgkmcnt(" #n ")" ::: "memory")
; #define PG8_BAR __builtin_amdgcn_s_barrier()
; #define PG8_SCHED __builtin_amdgcn_sched_barrier(0)
; template <class Epi>
; DI void gemm_phase(LAS unsigned char* lds, int tid, const Gemm g, const Order& S, const Epi& E) {
;     ...
;             PG8_LDA(At, 1, 1); PG8_STAGE(PG8_SB(1, 0), b3, voffB); PG8_STAGE(PG8_SB(1, 1), b3 + hstepB, voffB); PG8_STAGE(PG8_SA(1, 0), a3, voffA);
;             PG8_WAIT_V(8); PG8_WAIT_L(0); PG8_BAR; PG8_MMA(1, 0, At, B0); PG8_MMA(1, 1, At, B1); PG8_BAR; PG8_SCHED;
;         }
;         if (wr == 0) PG8_BAR;
	s_add_i32 s48, s51, s17
	v_lshl_add_u64 v[160:161], v[160:161], 0, s[24:25]
	s_mov_b32 m0, s48
	ds_read_b128 v[200:203], v147 offset:49152
	ds_read_b128 v[204:207], v147 offset:50176
	ds_read_b128 v[208:211], v147 offset:51200
	ds_read_b128 v[212:215], v147 offset:52224
	ds_read_b128 v[216:219], v147 offset:53248
	ds_read_b128 v[220:223], v147 offset:54272
	ds_read_b128 v[224:227], v147 offset:55296
	ds_read_b128 v[228:231], v147 offset:56320
	global_load_lds_dwordx4 v[160:161], off
	s_add_i32 m0, s48, 0x2000
	s_add_u32 s48, s76, 0x40080
	v_lshl_add_u64 v[160:161], v[178:179], 0, s[24:25]
	s_addc_u32 s49, s77, 0
	s_add_i32 s51, s52, s17
	global_load_lds_dwordx4 v[160:161], off
	v_lshl_add_u64 v[160:161], s[48:49], 0, v[0:1]
	s_mov_b32 m0, s51
	s_nop 0
	global_load_lds_dwordx4 v[160:161], off
	v_lshl_add_u64 v[160:161], s[48:49], 0, v[134:135]
	s_add_i32 m0, s51, 0x2000
	s_nop 0
	global_load_lds_dwordx4 v[160:161], off
	v_lshl_add_u64 v[160:161], v[188:189], 0, s[24:25]
	s_mov_b32 m0, s34
	s_nop 0
	global_load_lds_dwordx4 v[160:161], off
	v_lshl_add_u64 v[160:161], v[190:191], 0, s[24:25]
	s_mov_b32 m0, s36
	s_nop 0
	global_load_lds_dwordx4 v[160:161], off
	s_waitcnt vmcnt(8)
	s_waitcnt lgkmcnt(0)
	s_barrier
	s_setprio 1
	s_waitcnt lgkmcnt(0)
	v_mfma_f32_16x16x32_bf16 v[62:65], v[140:143], v[200:203], v[62:65]
	v_mfma_f32_16x16x32_bf16 v[58:61], v[152:155], v[200:203], v[58:61]
	v_mfma_f32_16x16x32_bf16 v[46:49], v[140:143], v[208:211], v[46:49]
	v_mfma_f32_16x16x32_bf16 v[42:45], v[152:155], v[208:211], v[42:45]
	v_mfma_f32_16x16x32_bf16 v[30:33], v[140:143], v[216:219], v[30:33]
	v_mfma_f32_16x16x32_bf16 v[26:29], v[152:155], v[216:219], v[26:29]
	v_mfma_f32_16x16x32_bf16 v[14:17], v[140:143], v[224:227], v[14:17]
	v_mfma_f32_16x16x32_bf16 v[10:13], v[152:155], v[224:227], v[10:13]
	v_mfma_f32_16x16x32_bf16 v[62:65], v[148:151], v[204:207], v[62:65]
	v_mfma_f32_16x16x32_bf16 v[58:61], v[156:159], v[204:207], v[58:61]
	v_mfma_f32_16x16x32_bf16 v[46:49], v[148:151], v[212:215], v[46:49]
	v_mfma_f32_16x16x32_bf16 v[42:45], v[156:159], v[212:215], v[42:45]
	v_mfma_f32_16x16x32_bf16 v[30:33], v[148:151], v[220:223], v[30:33]
	v_mfma_f32_16x16x32_bf16 v[26:29], v[156:159], v[220:223], v[26:29]
	v_mfma_f32_16x16x32_bf16 v[14:17], v[148:151], v[228:231], v[14:17]
	v_mfma_f32_16x16x32_bf16 v[10:13], v[156:159], v[228:231], v[10:13]
	v_mfma_f32_16x16x32_bf16 v[54:57], v[164:167], v[200:203], v[54:57]
	v_mfma_f32_16x16x32_bf16 v[50:53], v[174:177], v[200:203], v[50:53]
	v_mfma_f32_16x16x32_bf16 v[38:41], v[164:167], v[208:211], v[38:41]
	v_mfma_f32_16x16x32_bf16 v[34:37], v[174:177], v[208:211], v[34:37]
	v_mfma_f32_16x16x32_bf16 v[22:25], v[164:167], v[216:219], v[22:25]
	v_mfma_f32_16x16x32_bf16 v[18:21], v[174:177], v[216:219], v[18:21]
	v_mfma_f32_16x16x32_bf16 v[6:9], v[164:167], v[224:227], v[6:9]
	v_mfma_f32_16x16x32_bf16 v[2:5], v[174:177], v[224:227], v[2:5]
	v_mfma_f32_16x16x32_bf16 v[54:57], v[170:173], v[204:207], v[54:57]
	v_mfma_f32_16x16x32_bf16 v[50:53], v[196:199], v[204:207], v[50:53]
	v_mfma_f32_16x16x32_bf16 v[38:41], v[170:173], v[212:215], v[38:41]
	v_mfma_f32_16x16x32_bf16 v[34:37], v[196:199], v[212:215], v[34:37]
	v_mfma_f32_16x16x32_bf16 v[22:25], v[170:173], v[220:223], v[22:25]
	v_mfma_f32_16x16x32_bf16 v[18:21], v[196:199], v[220:223], v[18:21]
	v_mfma_f32_16x16x32_bf16 v[6:9], v[170:173], v[228:231], v[6:9]
	v_mfma_f32_16x16x32_bf16 v[2:5], v[196:199], v[228:231], v[2:5]
	s_setprio 0
	s_barrier
	s_add_i32 s47, s47, 2
	s_add_u32 s74, s74, 0x100
	s_addc_u32 s75, s75, 0
	s_add_u32 s45, s45, 0x100
	s_addc_u32 s46, s46, 0
	s_cmp_gt_u32 s47, 13
	s_cbranch_scc0 .LBB0_513
	s_and_b64 vcc, exec, s[8:9]
	s_cbranch_vccz .LBB0_516
	s_barrier
